# K loops: load segments at s_setprio 3, MFMA bursts at 0 without mid-burst toggles; saddr DMA; aligned loops; hand-written scan
# speedup vs baseline: 1.0146x; 1.0085x over previous
; #define PG8_STAGE(bufoff, gbase, voff) do { _Pragma("unroll") for (int _i = 0; _i < 2; ++_i) \
;         __builtin_amdgcn_global_load_lds((const unsigned*)((const char*)(gbase) + (voff)[_i]), (PG8_LAS unsigned*)(lds + (bufoff) + ldsw + _i * 8192), 16, 0, 0); } while (0)
; #define PG8_LDA(dst, b, h) do { _Pragma("unroll") for (int m = 0; m < 4; ++m) _Pragma("unroll") for (int k = 0; k < 2; ++k) dst[m][k] = *(const PG8_LAS bf16x8*)(lds + PG8_SA(b, h) + aoff + m * 2048 + k * 1024); } while (0)
; #define PG8_LDB(dst, b, h) do { _Pragma("unroll") for (int n = 0; n < 2; ++n) _Pragma("unroll") for (int k = 0; k < 2; ++k) dst[n][k] = *(const PG8_LAS bf16x8*)(lds + PG8_SB(b, h) + boff + n * 2048 + k * 1024); } while (0)
; template <class Epi, class Sched, bool ALIGN_EPI = false, bool SP2 = false>
; __device__ __forceinline__ void gemm_phase(PG8_LAS unsigned char* lds, const Gemm g, const Sched& S, const Epi& E) {
;     ...
;         for (int t = 0; t < nt; t += 2) {
;             const bool last = (t == nt - 2);
;             const char* a1 = cA + (size_t)(t + 1) * kstep;
;             const char* a2 = last ? nA : cA + (size_t)(t + 2) * kstep; const char* b2 = last ? nB : cB + (size_t)(t + 2) * kstep;
;             const char* a3 = a2 + kstep; const char* b3 = b2 + kstep;
;             if (last && has_next) S.a_ready(nxt);
;             if constexpr (SP2) {
;             PG8_LDB(B0, 0, 0); PG8_LDB(B1, 0, 1); PG8_SCHED; PG8_LDA(At, 0, 0); PG8_STAGE(PG8_SA(1, 1), a1 + hstep, voffA);
;             PG8_WAIT_V(8); PG8_WAIT_L(0); PG8_BAR; PG8_MMA(0, 0, At, B0); PG8_MMA(0, 1, At, B1); PG8_BAR; PG8_SCHED;
;             PG8_LDA(At, 0, 1); PG8_STAGE(PG8_SB(0, 0), b2, voffB); PG8_STAGE(PG8_SB(0, 1), b2 + hstep, voffB); PG8_STAGE(PG8_SA(0, 0), a2, voffA);
;             PG8_WAIT_V(8); PG8_WAIT_L(0); PG8_BAR; PG8_MMA(1, 0, At, B0); PG8_MMA(1, 1, At, B1); PG8_BAR; PG8_SCHED;
;             PG8_LDB(B0, 1, 0); PG8_LDB(B1, 1, 1); PG8_SCHED; PG8_LDA(At, 1, 0); PG8_STAGE(PG8_SA(0, 1), a2 + hstep, voffA);
;             PG8_WAIT_V(8); PG8_WAIT_L(0); PG8_BAR; PG8_MMA(0, 0, At, B0); PG8_MMA(0, 1, At, B1); PG8_BAR; PG8_SCHED;
;             PG8_LDA(At, 1, 1); PG8_STAGE(PG8_SB(1, 0), b3, voffB); PG8_STAGE(PG8_SB(1, 1), b3 + hstep, voffB); PG8_STAGE(PG8_SA(1, 0), a3, voffA);
;             PG8_WAIT_V(8); PG8_WAIT_L(0); PG8_BAR; PG8_MMA(1, 0, At, B0); PG8_MMA(1, 1, At, B1); PG8_BAR; PG8_SCHED;
.LBB0_301:
	s_add_u32 s38, s36, 0xfff80080
	s_addc_u32 s39, s37, -1
	s_add_i32 s61, 0, 0x10000
	s_cmp_eq_u32 s60, 28
	s_cselect_b32 s41, s11, s39
	s_cselect_b32 s40, s13, s38
	s_cselect_b32 s39, s56, s59
	s_cselect_b32 s38, s57, s58
	s_add_i32 s64, 0, 0x14000
	v_add_u32_e32 v158, s61, v150
	v_add_u32_e32 v162, s64, v150
	ds_read_b128 v[142:145], v158
	ds_read_b128 v[146:149], v158 offset:1024
	ds_read_b128 v[154:157], v158 offset:2048
	ds_read_b128 v[158:161], v158 offset:3072
	ds_read_b128 v[174:177], v162
	ds_read_b128 v[178:181], v162 offset:1024
	ds_read_b128 v[204:207], v162 offset:2048
	ds_read_b128 v[208:211], v162 offset:3072
	s_add_i32 m0, s47, 0xc000
	ds_read_b128 v[212:215], v153
	ds_read_b128 v[216:219], v153 offset:1024
	ds_read_b128 v[220:223], v153 offset:2048
	ds_read_b128 v[224:227], v153 offset:3072
	ds_read_b128 v[228:231], v153 offset:4096
	ds_read_b128 v[232:235], v153 offset:5120
	ds_read_b128 v[236:239], v153 offset:6144
	ds_read_b128 v[240:243], v153 offset:7168
	global_load_lds_dwordx4 v138, s[36:37]
	s_add_i32 m0, s47, 0xe000
	s_nop 0
	global_load_lds_dwordx4 v140, s[36:37]
	s_waitcnt vmcnt(8)
	s_waitcnt lgkmcnt(0)
	s_barrier
	s_setprio 0
	s_waitcnt lgkmcnt(0)
	v_mfma_f32_16x16x32_bf16 v[128:131], v[142:145], v[212:215], v[128:131]
	v_mfma_f32_16x16x32_bf16 v[120:123], v[154:157], v[212:215], v[120:123]
	v_mfma_f32_16x16x32_bf16 v[112:115], v[142:145], v[220:223], v[112:115]
	v_mfma_f32_16x16x32_bf16 v[104:107], v[154:157], v[220:223], v[104:107]
	v_mfma_f32_16x16x32_bf16 v[96:99], v[142:145], v[228:231], v[96:99]
	v_mfma_f32_16x16x32_bf16 v[88:91], v[154:157], v[228:231], v[88:91]
	v_mfma_f32_16x16x32_bf16 v[80:83], v[142:145], v[236:239], v[80:83]
	v_mfma_f32_16x16x32_bf16 v[72:75], v[154:157], v[236:239], v[72:75]
	v_mfma_f32_16x16x32_bf16 v[128:131], v[146:149], v[216:219], v[128:131]
	v_mfma_f32_16x16x32_bf16 v[120:123], v[158:161], v[216:219], v[120:123]
	v_mfma_f32_16x16x32_bf16 v[112:115], v[146:149], v[224:227], v[112:115]
	v_mfma_f32_16x16x32_bf16 v[104:107], v[158:161], v[224:227], v[104:107]
	v_mfma_f32_16x16x32_bf16 v[96:99], v[146:149], v[232:235], v[96:99]
	v_mfma_f32_16x16x32_bf16 v[88:91], v[158:161], v[232:235], v[88:91]
	v_mfma_f32_16x16x32_bf16 v[80:83], v[146:149], v[240:243], v[80:83]
	v_mfma_f32_16x16x32_bf16 v[72:75], v[158:161], v[240:243], v[72:75]
	v_mfma_f32_16x16x32_bf16 v[124:127], v[174:177], v[212:215], v[124:127]
	v_mfma_f32_16x16x32_bf16 v[116:119], v[204:207], v[212:215], v[116:119]
	v_mfma_f32_16x16x32_bf16 v[108:111], v[174:177], v[220:223], v[108:111]
	v_mfma_f32_16x16x32_bf16 v[100:103], v[204:207], v[220:223], v[100:103]
	v_mfma_f32_16x16x32_bf16 v[92:95], v[174:177], v[228:231], v[92:95]
	v_mfma_f32_16x16x32_bf16 v[84:87], v[204:207], v[228:231], v[84:87]
	v_mfma_f32_16x16x32_bf16 v[76:79], v[174:177], v[236:239], v[76:79]
	v_mfma_f32_16x16x32_bf16 v[68:71], v[204:207], v[236:239], v[68:71]
	v_mfma_f32_16x16x32_bf16 v[124:127], v[178:181], v[216:219], v[124:127]
	v_mfma_f32_16x16x32_bf16 v[116:119], v[208:211], v[216:219], v[116:119]
	v_mfma_f32_16x16x32_bf16 v[108:111], v[178:181], v[224:227], v[108:111]
	v_mfma_f32_16x16x32_bf16 v[100:103], v[208:211], v[224:227], v[100:103]
	v_mfma_f32_16x16x32_bf16 v[92:95], v[178:181], v[232:235], v[92:95]
	v_mfma_f32_16x16x32_bf16 v[84:87], v[208:211], v[232:235], v[84:87]
	v_mfma_f32_16x16x32_bf16 v[76:79], v[178:181], v[240:243], v[76:79]
	v_mfma_f32_16x16x32_bf16 v[68:71], v[208:211], v[240:243], v[68:71]
	s_setprio 3
	s_barrier
	s_add_i32 s61, s61, s42
	s_mov_b32 m0, s61
	ds_read_b128 v[212:215], v153 offset:16384
	ds_read_b128 v[216:219], v153 offset:17408
	ds_read_b128 v[220:223], v153 offset:18432
	ds_read_b128 v[224:227], v153 offset:19456
	ds_read_b128 v[228:231], v153 offset:20480
	ds_read_b128 v[232:235], v153 offset:21504
	ds_read_b128 v[236:239], v153 offset:22528
	ds_read_b128 v[240:243], v153 offset:23552
	global_load_lds_dwordx4 v2, s[38:39]
	s_add_i32 m0, s61, 0x2000
	s_add_u32 s62, s38, 0x80000
	s_addc_u32 s63, s39, 0
	s_add_i32 s61, s64, s42
	global_load_lds_dwordx4 v132, s[38:39]
	s_mov_b32 m0, s61
	s_nop 0
	global_load_lds_dwordx4 v2, s[62:63]
	s_add_i32 m0, s61, 0x2000
	s_nop 0
	global_load_lds_dwordx4 v132, s[62:63]
	s_mov_b32 m0, s47
	s_nop 0
	global_load_lds_dwordx4 v136, s[40:41]
	s_mov_b32 m0, s48
	s_nop 0
	global_load_lds_dwordx4 v134, s[40:41]
	s_waitcnt vmcnt(8)
	s_waitcnt lgkmcnt(0)
	s_barrier
	s_setprio 0
	s_waitcnt lgkmcnt(0)
	v_mfma_f32_16x16x32_bf16 v[64:67], v[142:145], v[212:215], v[64:67]
	v_mfma_f32_16x16x32_bf16 v[56:59], v[154:157], v[212:215], v[56:59]
	v_mfma_f32_16x16x32_bf16 v[48:51], v[142:145], v[220:223], v[48:51]
	v_mfma_f32_16x16x32_bf16 v[40:43], v[154:157], v[220:223], v[40:43]
	v_mfma_f32_16x16x32_bf16 v[32:35], v[142:145], v[228:231], v[32:35]
	v_mfma_f32_16x16x32_bf16 v[24:27], v[154:157], v[228:231], v[24:27]
	v_mfma_f32_16x16x32_bf16 v[16:19], v[142:145], v[236:239], v[16:19]
	v_mfma_f32_16x16x32_bf16 v[8:11], v[154:157], v[236:239], v[8:11]
	v_mfma_f32_16x16x32_bf16 v[64:67], v[146:149], v[216:219], v[64:67]
	v_mfma_f32_16x16x32_bf16 v[56:59], v[158:161], v[216:219], v[56:59]
	v_mfma_f32_16x16x32_bf16 v[48:51], v[146:149], v[224:227], v[48:51]
	v_mfma_f32_16x16x32_bf16 v[40:43], v[158:161], v[224:227], v[40:43]
	v_mfma_f32_16x16x32_bf16 v[32:35], v[146:149], v[232:235], v[32:35]
	v_mfma_f32_16x16x32_bf16 v[24:27], v[158:161], v[232:235], v[24:27]
	v_mfma_f32_16x16x32_bf16 v[16:19], v[146:149], v[240:243], v[16:19]
	v_mfma_f32_16x16x32_bf16 v[8:11], v[158:161], v[240:243], v[8:11]
	v_mfma_f32_16x16x32_bf16 v[60:63], v[174:177], v[212:215], v[60:63]
	v_mfma_f32_16x16x32_bf16 v[52:55], v[204:207], v[212:215], v[52:55]
	v_mfma_f32_16x16x32_bf16 v[44:47], v[174:177], v[220:223], v[44:47]
	v_mfma_f32_16x16x32_bf16 v[36:39], v[204:207], v[220:223], v[36:39]
	v_mfma_f32_16x16x32_bf16 v[28:31], v[174:177], v[228:231], v[28:31]
	v_mfma_f32_16x16x32_bf16 v[20:23], v[204:207], v[228:231], v[20:23]
	v_mfma_f32_16x16x32_bf16 v[12:15], v[174:177], v[236:239], v[12:15]
	v_mfma_f32_16x16x32_bf16 v[4:7], v[204:207], v[236:239], v[4:7]
	v_mfma_f32_16x16x32_bf16 v[60:63], v[178:181], v[216:219], v[60:63]
	v_mfma_f32_16x16x32_bf16 v[52:55], v[208:211], v[216:219], v[52:55]
	v_mfma_f32_16x16x32_bf16 v[44:47], v[178:181], v[224:227], v[44:47]
	v_mfma_f32_16x16x32_bf16 v[36:39], v[208:211], v[224:227], v[36:39]
	v_mfma_f32_16x16x32_bf16 v[28:31], v[178:181], v[232:235], v[28:31]
	v_mfma_f32_16x16x32_bf16 v[20:23], v[208:211], v[232:235], v[20:23]
	v_mfma_f32_16x16x32_bf16 v[12:15], v[178:181], v[240:243], v[12:15]
	v_mfma_f32_16x16x32_bf16 v[4:7], v[208:211], v[240:243], v[4:7]
	s_setprio 3
	s_barrier
; #define PG8_STAGE(bufoff, gbase, voff) do { _Pragma("unroll") for (int _i = 0; _i < 2; ++_i) \
;         __builtin_amdgcn_global_load_lds((const unsigned*)((const char*)(gbase) + (voff)[_i]), (PG8_LAS unsigned*)(lds + (bufoff) + ldsw + _i * 8192), 16, 0, 0); } while (0)
; #define PG8_LDA(dst, b, h) do { _Pragma("unroll") for (int m = 0; m < 4; ++m) _Pragma("unroll") for (int k = 0; k < 2; ++k) dst[m][k] = *(const PG8_LAS bf16x8*)(lds + PG8_SA(b, h) + aoff + m * 2048 + k * 1024); } while (0)
; #define PG8_LDB(dst, b, h) do { _Pragma("unroll") for (int n = 0; n < 2; ++n) _Pragma("unroll") for (int k = 0; k < 2; ++k) dst[n][k] = *(const PG8_LAS bf16x8*)(lds + PG8_SB(b, h) + boff + n * 2048 + k * 1024); } while (0)
; #define PG8_MMA(ai, bj, At, Bt) do { __builtin_amdgcn_s_setprio(1); _Pragma("unroll") for (int m = 0; m < 4; ++m) _Pragma("unroll") for (int n = 0; n < 2; ++n) _Pragma("unroll") for (int k = 0; k < 2; ++k) \
;         acc[ai][bj][m][n] = __builtin_amdgcn_mfma_f32_16x16x32_bf16(Bt[n][k], At[m][k], acc[ai][bj][m][n], 0, 0, 0); __builtin_amdgcn_s_setprio(0); } while (0)
; #define PG8_WAIT_V(n) asm volatile("s_waitcnt vmcnt(" #n ")" ::: "memory")
; #define PG8_WAIT_L(n) asm volatile("s_waitcnt lgkmcnt(" #n ")" ::: "memory")
; #define PG8_BAR __builtin_amdgcn_s_barrier()
; #define PG8_SCHED __builtin_amdgcn_sched_barrier(0)
; template <class Epi, class Sched, bool ALIGN_EPI = false, bool SP2 = false>
; __device__ __forceinline__ void gemm_phase(PG8_LAS unsigned char* lds, const Gemm g, const Sched& S, const Epi& E) {
;     ...
;             PG8_LDB(B0, 1, 0); PG8_LDB(B1, 1, 1); PG8_SCHED; PG8_LDA(At, 1, 0); PG8_STAGE(PG8_SA(0, 1), a2 + hstep, voffA);
;             PG8_WAIT_V(8); PG8_WAIT_L(0); PG8_BAR; PG8_MMA(0, 0, At, B0); PG8_MMA(0, 1, At, B1); PG8_BAR; PG8_SCHED;
;             PG8_LDA(At, 1, 1); PG8_STAGE(PG8_SB(1, 0), b3, voffB); PG8_STAGE(PG8_SB(1, 1), b3 + hstep, voffB); PG8_STAGE(PG8_SA(1, 0), a3, voffA);
;             PG8_WAIT_V(8); PG8_WAIT_L(0); PG8_BAR; PG8_MMA(1, 0, At, B0); PG8_MMA(1, 1, At, B1); PG8_BAR; PG8_SCHED;
	s_add_i32 s61, 0, 0x18000
	s_add_i32 s62, 0, 0x1c000
	v_add_u32_e32 v158, s61, v150
	v_add_u32_e32 v164, s62, v150
	ds_read_b128 v[142:145], v158
	ds_read_b128 v[146:149], v158 offset:1024
	ds_read_b128 v[154:157], v158 offset:2048
	ds_read_b128 v[158:161], v158 offset:3072
	ds_read_b128 v[174:177], v164
	ds_read_b128 v[178:181], v164 offset:1024
	ds_read_b128 v[204:207], v164 offset:2048
	ds_read_b128 v[208:211], v164 offset:3072
	s_add_u32 s100, s40, 0x80
	s_addc_u32 s101, s41, 0
	s_add_u32 s40, s40, 0x80000
	s_addc_u32 s41, s41, 0
	s_mov_b32 m0, s49
	ds_read_b128 v[212:215], v153 offset:32768
	ds_read_b128 v[216:219], v153 offset:33792
	ds_read_b128 v[220:223], v153 offset:34816
	ds_read_b128 v[224:227], v153 offset:35840
	ds_read_b128 v[228:231], v153 offset:36864
	ds_read_b128 v[232:235], v153 offset:37888
	ds_read_b128 v[236:239], v153 offset:38912
	ds_read_b128 v[240:243], v153 offset:39936
	global_load_lds_dwordx4 v136, s[40:41]
	s_mov_b32 m0, s50
	s_nop 0
	global_load_lds_dwordx4 v134, s[40:41]
	s_waitcnt vmcnt(8)
	s_waitcnt lgkmcnt(0)
	s_barrier
	s_setprio 0
	s_waitcnt lgkmcnt(0)
	v_mfma_f32_16x16x32_bf16 v[128:131], v[142:145], v[212:215], v[128:131]
	v_mfma_f32_16x16x32_bf16 v[120:123], v[154:157], v[212:215], v[120:123]
	v_mfma_f32_16x16x32_bf16 v[112:115], v[142:145], v[220:223], v[112:115]
	v_mfma_f32_16x16x32_bf16 v[104:107], v[154:157], v[220:223], v[104:107]
	v_mfma_f32_16x16x32_bf16 v[96:99], v[142:145], v[228:231], v[96:99]
	v_mfma_f32_16x16x32_bf16 v[88:91], v[154:157], v[228:231], v[88:91]
	v_mfma_f32_16x16x32_bf16 v[80:83], v[142:145], v[236:239], v[80:83]
	v_mfma_f32_16x16x32_bf16 v[72:75], v[154:157], v[236:239], v[72:75]
	v_mfma_f32_16x16x32_bf16 v[128:131], v[146:149], v[216:219], v[128:131]
	v_mfma_f32_16x16x32_bf16 v[120:123], v[158:161], v[216:219], v[120:123]
	v_mfma_f32_16x16x32_bf16 v[112:115], v[146:149], v[224:227], v[112:115]
	v_mfma_f32_16x16x32_bf16 v[104:107], v[158:161], v[224:227], v[104:107]
	v_mfma_f32_16x16x32_bf16 v[96:99], v[146:149], v[232:235], v[96:99]
	v_mfma_f32_16x16x32_bf16 v[88:91], v[158:161], v[232:235], v[88:91]
	v_mfma_f32_16x16x32_bf16 v[80:83], v[146:149], v[240:243], v[80:83]
	v_mfma_f32_16x16x32_bf16 v[72:75], v[158:161], v[240:243], v[72:75]
	v_mfma_f32_16x16x32_bf16 v[124:127], v[174:177], v[212:215], v[124:127]
	v_mfma_f32_16x16x32_bf16 v[116:119], v[204:207], v[212:215], v[116:119]
	v_mfma_f32_16x16x32_bf16 v[108:111], v[174:177], v[220:223], v[108:111]
	v_mfma_f32_16x16x32_bf16 v[100:103], v[204:207], v[220:223], v[100:103]
	v_mfma_f32_16x16x32_bf16 v[92:95], v[174:177], v[228:231], v[92:95]
	v_mfma_f32_16x16x32_bf16 v[84:87], v[204:207], v[228:231], v[84:87]
	v_mfma_f32_16x16x32_bf16 v[76:79], v[174:177], v[236:239], v[76:79]
	v_mfma_f32_16x16x32_bf16 v[68:71], v[204:207], v[236:239], v[68:71]
	v_mfma_f32_16x16x32_bf16 v[124:127], v[178:181], v[216:219], v[124:127]
	v_mfma_f32_16x16x32_bf16 v[116:119], v[208:211], v[216:219], v[116:119]
	v_mfma_f32_16x16x32_bf16 v[108:111], v[178:181], v[224:227], v[108:111]
	v_mfma_f32_16x16x32_bf16 v[100:103], v[208:211], v[224:227], v[100:103]
	v_mfma_f32_16x16x32_bf16 v[92:95], v[178:181], v[232:235], v[92:95]
	v_mfma_f32_16x16x32_bf16 v[84:87], v[208:211], v[232:235], v[84:87]
	v_mfma_f32_16x16x32_bf16 v[76:79], v[178:181], v[240:243], v[76:79]
	v_mfma_f32_16x16x32_bf16 v[68:71], v[208:211], v[240:243], v[68:71]
	s_setprio 3
	s_barrier
	s_add_i32 s40, s61, s42
	s_add_i32 m0, s40, 0xffffff80
	ds_read_b128 v[212:215], v153 offset:49152
	ds_read_b128 v[216:219], v153 offset:50176
	ds_read_b128 v[220:223], v153 offset:51200
	ds_read_b128 v[224:227], v153 offset:52224
	ds_read_b128 v[228:231], v153 offset:53248
	ds_read_b128 v[232:235], v153 offset:54272
	ds_read_b128 v[236:239], v153 offset:55296
	ds_read_b128 v[240:243], v153 offset:56320
	global_load_lds_dwordx4 v2, s[38:39] offset:128
	s_add_i32 m0, s40, 0x1f80
	s_add_i32 s40, s62, s42
	global_load_lds_dwordx4 v132, s[38:39] offset:128
	s_add_u32 s38, s38, 0x80080
	s_addc_u32 s39, s39, 0
	s_mov_b32 m0, s40
	s_nop 0
	global_load_lds_dwordx4 v2, s[38:39]
	s_add_i32 m0, s40, 0x2000
	s_nop 0
	global_load_lds_dwordx4 v132, s[38:39]
	s_mov_b32 m0, s51
	s_nop 0
	global_load_lds_dwordx4 v136, s[100:101]
	s_mov_b32 m0, s53
	s_nop 0
	global_load_lds_dwordx4 v134, s[100:101]
	s_nop 0
	s_waitcnt vmcnt(8)
	s_waitcnt lgkmcnt(0)
	s_barrier
	s_setprio 0
	s_waitcnt lgkmcnt(0)
	v_mfma_f32_16x16x32_bf16 v[64:67], v[142:145], v[212:215], v[64:67]
	v_mfma_f32_16x16x32_bf16 v[56:59], v[154:157], v[212:215], v[56:59]
	v_mfma_f32_16x16x32_bf16 v[48:51], v[142:145], v[220:223], v[48:51]
	v_mfma_f32_16x16x32_bf16 v[40:43], v[154:157], v[220:223], v[40:43]
	v_mfma_f32_16x16x32_bf16 v[32:35], v[142:145], v[228:231], v[32:35]
	v_mfma_f32_16x16x32_bf16 v[24:27], v[154:157], v[228:231], v[24:27]
	v_mfma_f32_16x16x32_bf16 v[16:19], v[142:145], v[236:239], v[16:19]
	v_mfma_f32_16x16x32_bf16 v[8:11], v[154:157], v[236:239], v[8:11]
	v_mfma_f32_16x16x32_bf16 v[64:67], v[146:149], v[216:219], v[64:67]
	v_mfma_f32_16x16x32_bf16 v[56:59], v[158:161], v[216:219], v[56:59]
	v_mfma_f32_16x16x32_bf16 v[48:51], v[146:149], v[224:227], v[48:51]
	v_mfma_f32_16x16x32_bf16 v[40:43], v[158:161], v[224:227], v[40:43]
	v_mfma_f32_16x16x32_bf16 v[32:35], v[146:149], v[232:235], v[32:35]
	v_mfma_f32_16x16x32_bf16 v[24:27], v[158:161], v[232:235], v[24:27]
	v_mfma_f32_16x16x32_bf16 v[16:19], v[146:149], v[240:243], v[16:19]
	v_mfma_f32_16x16x32_bf16 v[8:11], v[158:161], v[240:243], v[8:11]
	v_mfma_f32_16x16x32_bf16 v[60:63], v[174:177], v[212:215], v[60:63]
	v_mfma_f32_16x16x32_bf16 v[52:55], v[204:207], v[212:215], v[52:55]
	v_mfma_f32_16x16x32_bf16 v[44:47], v[174:177], v[220:223], v[44:47]
	v_mfma_f32_16x16x32_bf16 v[36:39], v[204:207], v[220:223], v[36:39]
	v_mfma_f32_16x16x32_bf16 v[28:31], v[174:177], v[228:231], v[28:31]
	v_mfma_f32_16x16x32_bf16 v[20:23], v[204:207], v[228:231], v[20:23]
	v_mfma_f32_16x16x32_bf16 v[12:15], v[174:177], v[236:239], v[12:15]
	v_mfma_f32_16x16x32_bf16 v[4:7], v[204:207], v[236:239], v[4:7]
	v_mfma_f32_16x16x32_bf16 v[60:63], v[178:181], v[216:219], v[60:63]
	v_mfma_f32_16x16x32_bf16 v[52:55], v[208:211], v[216:219], v[52:55]
	v_mfma_f32_16x16x32_bf16 v[44:47], v[178:181], v[224:227], v[44:47]
	v_mfma_f32_16x16x32_bf16 v[36:39], v[208:211], v[224:227], v[36:39]
	v_mfma_f32_16x16x32_bf16 v[28:31], v[178:181], v[232:235], v[28:31]
	v_mfma_f32_16x16x32_bf16 v[20:23], v[208:211], v[232:235], v[20:23]
	v_mfma_f32_16x16x32_bf16 v[12:15], v[178:181], v[240:243], v[12:15]
	v_mfma_f32_16x16x32_bf16 v[4:7], v[208:211], v[240:243], v[4:7]
	s_setprio 3
	s_barrier
	s_add_i32 s60, s60, 2
	s_add_u32 s36, s36, 0x100
	s_addc_u32 s37, s37, 0
	s_add_u32 s58, s58, 0x100
	s_addc_u32 s59, s59, 0
	s_cmp_gt_u32 s60, 29
	s_cbranch_scc0 .LBB0_301
	s_and_b64 vcc, exec, s[8:9]
	s_cbranch_vccz .LBB0_304
	s_barrier

; #define PG8_STAGE(bufoff, gbase, voff) do { _Pragma("unroll") for (int _i = 0; _i < 2; ++_i) \
;         __builtin_amdgcn_global_load_lds((const unsigned*)((const char*)(gbase) + (voff)[_i]), (PG8_LAS unsigned*)(lds + (bufoff) + ldsw + _i * 8192), 16, 0, 0); } while (0)
; #define PG8_LDA(dst, b, h) do { _Pragma("unroll") for (int m = 0; m < 4; ++m) _Pragma("unroll") for (int k = 0; k < 2; ++k) dst[m][k] = *(const PG8_LAS bf16x8*)(lds + PG8_SA(b, h) + aoff + m * 2048 + k * 1024); } while (0)
; #define PG8_LDB(dst, b, h) do { _Pragma("unroll") for (int n = 0; n < 2; ++n) _Pragma("unroll") for (int k = 0; k < 2; ++k) dst[n][k] = *(const PG8_LAS bf16x8*)(lds + PG8_SB(b, h) + boff + n * 2048 + k * 1024); } while (0)
; #define PG8_MMA(ai, bj, At, Bt) do { __builtin_amdgcn_s_setprio(1); _Pragma("unroll") for (int m = 0; m < 4; ++m) _Pragma("unroll") for (int n = 0; n < 2; ++n) _Pragma("unroll") for (int k = 0; k < 2; ++k) \
;         acc[ai][bj][m][n] = __builtin_amdgcn_mfma_f32_16x16x32_bf16(Bt[n][k], At[m][k], acc[ai][bj][m][n], 0, 0, 0); __builtin_amdgcn_s_setprio(0); } while (0)
; #define PG8_WAIT_V(n) asm volatile("s_waitcnt vmcnt(" #n ")" ::: "memory")
; #define PG8_WAIT_L(n) asm volatile("s_waitcnt lgkmcnt(" #n ")" ::: "memory")
; template <class Epi, class Sched, bool ALIGN_EPI = false, bool SP2 = false>
; __device__ __forceinline__ void gemm_phase(PG8_LAS unsigned char* lds, const Gemm g, const Sched& S, const Epi& E) {
;     ...
;             const bool last = (t == nt - 2);
;             const char* a1 = cA + (size_t)(t + 1) * kstep;
;             const char* a2 = last ? nA : cA + (size_t)(t + 2) * kstep; const char* b2 = last ? nB : cB + (size_t)(t + 2) * kstep;
;             const char* a3 = a2 + kstep; const char* b3 = b2 + kstep;
;             if (last && has_next) S.a_ready(nxt);
;             if constexpr (SP2) {
;             PG8_LDB(B0, 0, 0); PG8_LDB(B1, 0, 1); PG8_SCHED; PG8_LDA(At, 0, 0); PG8_STAGE(PG8_SA(1, 1), a1 + hstep, voffA);
;             PG8_WAIT_V(8); PG8_WAIT_L(0); PG8_BAR; PG8_MMA(0, 0, At, B0); PG8_MMA(0, 1, At, B1); PG8_BAR; PG8_SCHED;
;             PG8_LDA(At, 0, 1); PG8_STAGE(PG8_SB(0, 0), b2, voffB); PG8_STAGE(PG8_SB(0, 1), b2 + hstep, voffB); PG8_STAGE(PG8_SA(0, 0), a2, voffA);
;             PG8_WAIT_V(8); PG8_WAIT_L(0); PG8_BAR; PG8_MMA(1, 0, At, B0); PG8_MMA(1, 1, At, B1); PG8_BAR; PG8_SCHED;
.LBB0_575:
	s_add_u32 s36, s34, 0x100
	s_addc_u32 s37, s35, 0
	s_add_i32 s64, 0, 0x10000
	s_cmpk_eq_i32 s63, 0x52
	s_cselect_b32 s41, s5, s37
	s_cselect_b32 s40, s4, s36
	v_add_u32_e32 v135, s64, v173
	s_cselect_b32 s39, s31, s62
	s_cselect_b32 s38, s30, s61
	s_add_i32 s65, 0, 0x14000
	ds_read_b128 v[142:145], v135
	ds_read_b128 v[146:149], v135 offset:1024
	ds_read_b128 v[150:153], v135 offset:2048
	ds_read_b128 v[154:157], v135 offset:3072
	v_add_u32_e32 v135, s65, v173
	ds_read_b128 v[158:161], v135
	ds_read_b128 v[174:177], v135 offset:1024
	ds_read_b128 v[180:183], v135 offset:2048
	ds_read_b128 v[204:207], v135 offset:3072
	v_lshl_add_u64 v[162:163], s[34:35], 0, v[138:139]
	s_add_i32 m0, s47, 0xc000
	ds_read_b128 v[208:211], v179
	ds_read_b128 v[212:215], v179 offset:1024
	ds_read_b128 v[216:219], v179 offset:2048
	ds_read_b128 v[220:223], v179 offset:3072
	ds_read_b128 v[224:227], v179 offset:4096
	ds_read_b128 v[228:231], v179 offset:5120
	ds_read_b128 v[232:235], v179 offset:6144
	ds_read_b128 v[236:239], v179 offset:7168
	global_load_lds_dwordx4 v[162:163], off
	v_lshl_add_u64 v[162:163], s[34:35], 0, v[140:141]
	s_add_i32 m0, s47, 0xe000
	s_nop 0
	global_load_lds_dwordx4 v[162:163], off
	s_waitcnt vmcnt(8)
	s_waitcnt lgkmcnt(0)
	s_barrier
	s_setprio 0
	s_waitcnt lgkmcnt(0)
	v_mfma_f32_16x16x32_bf16 v[128:131], v[142:145], v[208:211], v[128:131]
	v_mfma_f32_16x16x32_bf16 v[124:127], v[150:153], v[208:211], v[124:127]
	v_mfma_f32_16x16x32_bf16 v[112:115], v[142:145], v[216:219], v[112:115]
	v_mfma_f32_16x16x32_bf16 v[108:111], v[150:153], v[216:219], v[108:111]
	v_mfma_f32_16x16x32_bf16 v[96:99], v[142:145], v[224:227], v[96:99]
	v_mfma_f32_16x16x32_bf16 v[92:95], v[150:153], v[224:227], v[92:95]
	v_mfma_f32_16x16x32_bf16 v[80:83], v[142:145], v[232:235], v[80:83]
	v_mfma_f32_16x16x32_bf16 v[76:79], v[150:153], v[232:235], v[76:79]
	v_mfma_f32_16x16x32_bf16 v[128:131], v[146:149], v[212:215], v[128:131]
	v_mfma_f32_16x16x32_bf16 v[124:127], v[154:157], v[212:215], v[124:127]
	v_mfma_f32_16x16x32_bf16 v[112:115], v[146:149], v[220:223], v[112:115]
	v_mfma_f32_16x16x32_bf16 v[108:111], v[154:157], v[220:223], v[108:111]
	v_mfma_f32_16x16x32_bf16 v[96:99], v[146:149], v[228:231], v[96:99]
	v_mfma_f32_16x16x32_bf16 v[92:95], v[154:157], v[228:231], v[92:95]
	v_mfma_f32_16x16x32_bf16 v[80:83], v[146:149], v[236:239], v[80:83]
	v_mfma_f32_16x16x32_bf16 v[76:79], v[154:157], v[236:239], v[76:79]
	v_mfma_f32_16x16x32_bf16 v[120:123], v[158:161], v[208:211], v[120:123]
	v_mfma_f32_16x16x32_bf16 v[116:119], v[180:183], v[208:211], v[116:119]
	v_mfma_f32_16x16x32_bf16 v[104:107], v[158:161], v[216:219], v[104:107]
	v_mfma_f32_16x16x32_bf16 v[100:103], v[180:183], v[216:219], v[100:103]
	v_mfma_f32_16x16x32_bf16 v[88:91], v[158:161], v[224:227], v[88:91]
	v_mfma_f32_16x16x32_bf16 v[84:87], v[180:183], v[224:227], v[84:87]
	v_mfma_f32_16x16x32_bf16 v[72:75], v[158:161], v[232:235], v[72:75]
	v_mfma_f32_16x16x32_bf16 v[68:71], v[180:183], v[232:235], v[68:71]
	v_mfma_f32_16x16x32_bf16 v[120:123], v[174:177], v[212:215], v[120:123]
	v_mfma_f32_16x16x32_bf16 v[116:119], v[204:207], v[212:215], v[116:119]
	v_mfma_f32_16x16x32_bf16 v[104:107], v[174:177], v[220:223], v[104:107]
	v_mfma_f32_16x16x32_bf16 v[100:103], v[204:207], v[220:223], v[100:103]
	v_mfma_f32_16x16x32_bf16 v[88:91], v[174:177], v[228:231], v[88:91]
	v_mfma_f32_16x16x32_bf16 v[84:87], v[204:207], v[228:231], v[84:87]
	v_mfma_f32_16x16x32_bf16 v[72:75], v[174:177], v[236:239], v[72:75]
	v_mfma_f32_16x16x32_bf16 v[68:71], v[204:207], v[236:239], v[68:71]
	s_setprio 3
	s_barrier
	s_add_i32 s34, s64, s46
	s_mov_b32 m0, s34
	ds_read_b128 v[208:211], v179 offset:16384
	ds_read_b128 v[212:215], v179 offset:17408
	ds_read_b128 v[216:219], v179 offset:18432
	ds_read_b128 v[220:223], v179 offset:19456
	ds_read_b128 v[224:227], v179 offset:20480
	ds_read_b128 v[228:231], v179 offset:21504
	ds_read_b128 v[232:235], v179 offset:22528
	ds_read_b128 v[236:239], v179 offset:23552
	global_load_lds_dwordx4 v2, s[38:39]
	s_add_i32 m0, s34, 0x2000
	s_add_u32 s34, s38, 0x158000
	s_addc_u32 s35, s39, 0
	s_add_i32 s64, s65, s46
	global_load_lds_dwordx4 v132, s[38:39]
	s_mov_b32 m0, s64
	s_nop 0
	global_load_lds_dwordx4 v2, s[34:35]
	s_add_i32 m0, s64, 0x2000
	s_nop 0
	global_load_lds_dwordx4 v132, s[34:35]
	s_mov_b32 m0, s47
	s_nop 0
	global_load_lds_dwordx4 v2, s[40:41]
	s_mov_b32 m0, s48
	s_nop 0
	global_load_lds_dwordx4 v132, s[40:41]
	s_waitcnt vmcnt(8)
	s_waitcnt lgkmcnt(0)
	s_barrier
	s_setprio 0
	s_waitcnt lgkmcnt(0)
	v_mfma_f32_16x16x32_bf16 v[64:67], v[142:145], v[208:211], v[64:67]
	v_mfma_f32_16x16x32_bf16 v[60:63], v[150:153], v[208:211], v[60:63]
	v_mfma_f32_16x16x32_bf16 v[48:51], v[142:145], v[216:219], v[48:51]
	v_mfma_f32_16x16x32_bf16 v[44:47], v[150:153], v[216:219], v[44:47]
	v_mfma_f32_16x16x32_bf16 v[32:35], v[142:145], v[224:227], v[32:35]
	v_mfma_f32_16x16x32_bf16 v[28:31], v[150:153], v[224:227], v[28:31]
	v_mfma_f32_16x16x32_bf16 v[16:19], v[142:145], v[232:235], v[16:19]
	v_mfma_f32_16x16x32_bf16 v[12:15], v[150:153], v[232:235], v[12:15]
	v_mfma_f32_16x16x32_bf16 v[64:67], v[146:149], v[212:215], v[64:67]
	v_mfma_f32_16x16x32_bf16 v[60:63], v[154:157], v[212:215], v[60:63]
	v_mfma_f32_16x16x32_bf16 v[48:51], v[146:149], v[220:223], v[48:51]
	v_mfma_f32_16x16x32_bf16 v[44:47], v[154:157], v[220:223], v[44:47]
	v_mfma_f32_16x16x32_bf16 v[32:35], v[146:149], v[228:231], v[32:35]
	v_mfma_f32_16x16x32_bf16 v[28:31], v[154:157], v[228:231], v[28:31]
	v_mfma_f32_16x16x32_bf16 v[16:19], v[146:149], v[236:239], v[16:19]
	v_mfma_f32_16x16x32_bf16 v[12:15], v[154:157], v[236:239], v[12:15]
	v_mfma_f32_16x16x32_bf16 v[56:59], v[158:161], v[208:211], v[56:59]
	v_mfma_f32_16x16x32_bf16 v[52:55], v[180:183], v[208:211], v[52:55]
	v_mfma_f32_16x16x32_bf16 v[40:43], v[158:161], v[216:219], v[40:43]
	v_mfma_f32_16x16x32_bf16 v[36:39], v[180:183], v[216:219], v[36:39]
	v_mfma_f32_16x16x32_bf16 v[24:27], v[158:161], v[224:227], v[24:27]
	v_mfma_f32_16x16x32_bf16 v[20:23], v[180:183], v[224:227], v[20:23]
	v_mfma_f32_16x16x32_bf16 v[8:11], v[158:161], v[232:235], v[8:11]
	v_mfma_f32_16x16x32_bf16 v[4:7], v[180:183], v[232:235], v[4:7]
	v_mfma_f32_16x16x32_bf16 v[56:59], v[174:177], v[212:215], v[56:59]
	v_mfma_f32_16x16x32_bf16 v[52:55], v[204:207], v[212:215], v[52:55]
	v_mfma_f32_16x16x32_bf16 v[40:43], v[174:177], v[220:223], v[40:43]
	v_mfma_f32_16x16x32_bf16 v[36:39], v[204:207], v[220:223], v[36:39]
	v_mfma_f32_16x16x32_bf16 v[24:27], v[174:177], v[228:231], v[24:27]
	v_mfma_f32_16x16x32_bf16 v[20:23], v[204:207], v[228:231], v[20:23]
	v_mfma_f32_16x16x32_bf16 v[8:11], v[174:177], v[236:239], v[8:11]
	v_mfma_f32_16x16x32_bf16 v[4:7], v[204:207], v[236:239], v[4:7]
	s_setprio 3
	s_barrier
; #define PG8_STAGE(bufoff, gbase, voff) do { _Pragma("unroll") for (int _i = 0; _i < 2; ++_i) \
;         __builtin_amdgcn_global_load_lds((const unsigned*)((const char*)(gbase) + (voff)[_i]), (PG8_LAS unsigned*)(lds + (bufoff) + ldsw + _i * 8192), 16, 0, 0); } while (0)
; #define PG8_LDA(dst, b, h) do { _Pragma("unroll") for (int m = 0; m < 4; ++m) _Pragma("unroll") for (int k = 0; k < 2; ++k) dst[m][k] = *(const PG8_LAS bf16x8*)(lds + PG8_SA(b, h) + aoff + m * 2048 + k * 1024); } while (0)
; #define PG8_LDB(dst, b, h) do { _Pragma("unroll") for (int n = 0; n < 2; ++n) _Pragma("unroll") for (int k = 0; k < 2; ++k) dst[n][k] = *(const PG8_LAS bf16x8*)(lds + PG8_SB(b, h) + boff + n * 2048 + k * 1024); } while (0)
; #define PG8_MMA(ai, bj, At, Bt) do { __builtin_amdgcn_s_setprio(1); _Pragma("unroll") for (int m = 0; m < 4; ++m) _Pragma("unroll") for (int n = 0; n < 2; ++n) _Pragma("unroll") for (int k = 0; k < 2; ++k) \
;         acc[ai][bj][m][n] = __builtin_amdgcn_mfma_f32_16x16x32_bf16(Bt[n][k], At[m][k], acc[ai][bj][m][n], 0, 0, 0); __builtin_amdgcn_s_setprio(0); } while (0)
; #define PG8_WAIT_V(n) asm volatile("s_waitcnt vmcnt(" #n ")" ::: "memory")
; #define PG8_WAIT_L(n) asm volatile("s_waitcnt lgkmcnt(" #n ")" ::: "memory")
; #define PG8_BAR __builtin_amdgcn_s_barrier()
; #define PG8_SCHED __builtin_amdgcn_sched_barrier(0)
; template <class Epi, class Sched, bool ALIGN_EPI = false, bool SP2 = false>
; __device__ __forceinline__ void gemm_phase(PG8_LAS unsigned char* lds, const Gemm g, const Sched& S, const Epi& E) {
;     ...
;             PG8_LDB(B0, 1, 0); PG8_LDB(B1, 1, 1); PG8_SCHED; PG8_LDA(At, 1, 0); PG8_STAGE(PG8_SA(0, 1), a2 + hstep, voffA);
;             PG8_WAIT_V(8); PG8_WAIT_L(0); PG8_BAR; PG8_MMA(0, 0, At, B0); PG8_MMA(0, 1, At, B1); PG8_BAR; PG8_SCHED;
;             PG8_LDA(At, 1, 1); PG8_STAGE(PG8_SB(1, 0), b3, voffB); PG8_STAGE(PG8_SB(1, 1), b3 + hstep, voffB); PG8_STAGE(PG8_SA(1, 0), a3, voffA);
;             PG8_WAIT_V(8); PG8_WAIT_L(0); PG8_BAR; PG8_MMA(1, 0, At, B0); PG8_MMA(1, 1, At, B1); PG8_BAR; PG8_SCHED;
	s_add_i32 s64, 0, 0x18000
	v_add_u32_e32 v135, s64, v173
	s_add_i32 s65, 0, 0x1c000
	ds_read_b128 v[142:145], v135
	ds_read_b128 v[146:149], v135 offset:1024
	ds_read_b128 v[150:153], v135 offset:2048
	ds_read_b128 v[154:157], v135 offset:3072
	v_add_u32_e32 v135, s65, v173
	ds_read_b128 v[158:161], v135
	ds_read_b128 v[174:177], v135 offset:1024
	ds_read_b128 v[180:183], v135 offset:2048
	ds_read_b128 v[204:207], v135 offset:3072
	s_add_u32 s34, s40, 0x158000
	s_addc_u32 s35, s41, 0
	s_mov_b32 m0, s49
	ds_read_b128 v[208:211], v179 offset:32768
	ds_read_b128 v[212:215], v179 offset:33792
	ds_read_b128 v[216:219], v179 offset:34816
	ds_read_b128 v[220:223], v179 offset:35840
	ds_read_b128 v[224:227], v179 offset:36864
	ds_read_b128 v[228:231], v179 offset:37888
	ds_read_b128 v[232:235], v179 offset:38912
	ds_read_b128 v[236:239], v179 offset:39936
	global_load_lds_dwordx4 v2, s[34:35]
	s_mov_b32 m0, s50
	s_nop 0
	global_load_lds_dwordx4 v132, s[34:35]
	s_nop 0
	s_waitcnt vmcnt(8)
	s_waitcnt lgkmcnt(0)
	s_barrier
	s_setprio 0
	s_waitcnt lgkmcnt(0)
	v_mfma_f32_16x16x32_bf16 v[128:131], v[142:145], v[208:211], v[128:131]
	v_mfma_f32_16x16x32_bf16 v[124:127], v[150:153], v[208:211], v[124:127]
	v_mfma_f32_16x16x32_bf16 v[112:115], v[142:145], v[216:219], v[112:115]
	v_mfma_f32_16x16x32_bf16 v[108:111], v[150:153], v[216:219], v[108:111]
	v_mfma_f32_16x16x32_bf16 v[96:99], v[142:145], v[224:227], v[96:99]
	v_mfma_f32_16x16x32_bf16 v[92:95], v[150:153], v[224:227], v[92:95]
	v_mfma_f32_16x16x32_bf16 v[80:83], v[142:145], v[232:235], v[80:83]
	v_mfma_f32_16x16x32_bf16 v[76:79], v[150:153], v[232:235], v[76:79]
	v_mfma_f32_16x16x32_bf16 v[128:131], v[146:149], v[212:215], v[128:131]
	v_mfma_f32_16x16x32_bf16 v[124:127], v[154:157], v[212:215], v[124:127]
	v_mfma_f32_16x16x32_bf16 v[112:115], v[146:149], v[220:223], v[112:115]
	v_mfma_f32_16x16x32_bf16 v[108:111], v[154:157], v[220:223], v[108:111]
	v_mfma_f32_16x16x32_bf16 v[96:99], v[146:149], v[228:231], v[96:99]
	v_mfma_f32_16x16x32_bf16 v[92:95], v[154:157], v[228:231], v[92:95]
	v_mfma_f32_16x16x32_bf16 v[80:83], v[146:149], v[236:239], v[80:83]
	v_mfma_f32_16x16x32_bf16 v[76:79], v[154:157], v[236:239], v[76:79]
	v_mfma_f32_16x16x32_bf16 v[120:123], v[158:161], v[208:211], v[120:123]
	v_mfma_f32_16x16x32_bf16 v[116:119], v[180:183], v[208:211], v[116:119]
	v_mfma_f32_16x16x32_bf16 v[104:107], v[158:161], v[216:219], v[104:107]
	v_mfma_f32_16x16x32_bf16 v[100:103], v[180:183], v[216:219], v[100:103]
	v_mfma_f32_16x16x32_bf16 v[88:91], v[158:161], v[224:227], v[88:91]
	v_mfma_f32_16x16x32_bf16 v[84:87], v[180:183], v[224:227], v[84:87]
	v_mfma_f32_16x16x32_bf16 v[72:75], v[158:161], v[232:235], v[72:75]
	v_mfma_f32_16x16x32_bf16 v[68:71], v[180:183], v[232:235], v[68:71]
	v_mfma_f32_16x16x32_bf16 v[120:123], v[174:177], v[212:215], v[120:123]
	v_mfma_f32_16x16x32_bf16 v[116:119], v[204:207], v[212:215], v[116:119]
	v_mfma_f32_16x16x32_bf16 v[104:107], v[174:177], v[220:223], v[104:107]
	v_mfma_f32_16x16x32_bf16 v[100:103], v[204:207], v[220:223], v[100:103]
	v_mfma_f32_16x16x32_bf16 v[88:91], v[174:177], v[228:231], v[88:91]
	v_mfma_f32_16x16x32_bf16 v[84:87], v[204:207], v[228:231], v[84:87]
	v_mfma_f32_16x16x32_bf16 v[72:75], v[174:177], v[236:239], v[72:75]
	v_mfma_f32_16x16x32_bf16 v[68:71], v[204:207], v[236:239], v[68:71]
	s_setprio 3
	s_barrier
	s_add_i32 s34, s64, s46
	s_add_i32 m0, s34, 0xffffff80
	ds_read_b128 v[208:211], v179 offset:49152
	ds_read_b128 v[212:215], v179 offset:50176
	ds_read_b128 v[216:219], v179 offset:51200
	ds_read_b128 v[220:223], v179 offset:52224
	ds_read_b128 v[224:227], v179 offset:53248
	ds_read_b128 v[228:231], v179 offset:54272
	ds_read_b128 v[232:235], v179 offset:55296
	ds_read_b128 v[236:239], v179 offset:56320
	global_load_lds_dwordx4 v2, s[38:39] offset:128
	s_add_i32 m0, s34, 0x1f80
	s_add_u32 s34, s38, 0x158080
	s_addc_u32 s35, s39, 0
	global_load_lds_dwordx4 v132, s[38:39] offset:128
	s_add_i32 s38, s65, s46
	s_mov_b32 m0, s38
	s_nop 0
	global_load_lds_dwordx4 v2, s[34:35]
	s_add_i32 m0, s38, 0x2000
	s_nop 0
	global_load_lds_dwordx4 v132, s[34:35]
	s_add_i32 m0, s53, 0xffffff80
	s_nop 0
	global_load_lds_dwordx4 v2, s[40:41] offset:128
	s_add_i32 m0, s54, 0xffffff80
	s_nop 0
	global_load_lds_dwordx4 v132, s[40:41] offset:128
	s_nop 0
	s_waitcnt vmcnt(8)
	s_waitcnt lgkmcnt(0)
	s_barrier
	s_setprio 0
	s_waitcnt lgkmcnt(0)
	v_mfma_f32_16x16x32_bf16 v[64:67], v[142:145], v[208:211], v[64:67]
	v_mfma_f32_16x16x32_bf16 v[60:63], v[150:153], v[208:211], v[60:63]
	v_mfma_f32_16x16x32_bf16 v[48:51], v[142:145], v[216:219], v[48:51]
	v_mfma_f32_16x16x32_bf16 v[44:47], v[150:153], v[216:219], v[44:47]
	v_mfma_f32_16x16x32_bf16 v[32:35], v[142:145], v[224:227], v[32:35]
	v_mfma_f32_16x16x32_bf16 v[28:31], v[150:153], v[224:227], v[28:31]
	v_mfma_f32_16x16x32_bf16 v[16:19], v[142:145], v[232:235], v[16:19]
	v_mfma_f32_16x16x32_bf16 v[12:15], v[150:153], v[232:235], v[12:15]
	v_mfma_f32_16x16x32_bf16 v[64:67], v[146:149], v[212:215], v[64:67]
	v_mfma_f32_16x16x32_bf16 v[60:63], v[154:157], v[212:215], v[60:63]
	v_mfma_f32_16x16x32_bf16 v[48:51], v[146:149], v[220:223], v[48:51]
	v_mfma_f32_16x16x32_bf16 v[44:47], v[154:157], v[220:223], v[44:47]
	v_mfma_f32_16x16x32_bf16 v[32:35], v[146:149], v[228:231], v[32:35]
	v_mfma_f32_16x16x32_bf16 v[28:31], v[154:157], v[228:231], v[28:31]
	v_mfma_f32_16x16x32_bf16 v[16:19], v[146:149], v[236:239], v[16:19]
	v_mfma_f32_16x16x32_bf16 v[12:15], v[154:157], v[236:239], v[12:15]
	v_mfma_f32_16x16x32_bf16 v[56:59], v[158:161], v[208:211], v[56:59]
	v_mfma_f32_16x16x32_bf16 v[52:55], v[180:183], v[208:211], v[52:55]
	v_mfma_f32_16x16x32_bf16 v[40:43], v[158:161], v[216:219], v[40:43]
	v_mfma_f32_16x16x32_bf16 v[36:39], v[180:183], v[216:219], v[36:39]
	v_mfma_f32_16x16x32_bf16 v[24:27], v[158:161], v[224:227], v[24:27]
	v_mfma_f32_16x16x32_bf16 v[20:23], v[180:183], v[224:227], v[20:23]
	v_mfma_f32_16x16x32_bf16 v[8:11], v[158:161], v[232:235], v[8:11]
	v_mfma_f32_16x16x32_bf16 v[4:7], v[180:183], v[232:235], v[4:7]
	v_mfma_f32_16x16x32_bf16 v[56:59], v[174:177], v[212:215], v[56:59]
	v_mfma_f32_16x16x32_bf16 v[52:55], v[204:207], v[212:215], v[52:55]
	v_mfma_f32_16x16x32_bf16 v[40:43], v[174:177], v[220:223], v[40:43]
	v_mfma_f32_16x16x32_bf16 v[36:39], v[204:207], v[220:223], v[36:39]
	v_mfma_f32_16x16x32_bf16 v[24:27], v[174:177], v[228:231], v[24:27]
	v_mfma_f32_16x16x32_bf16 v[20:23], v[204:207], v[228:231], v[20:23]
	v_mfma_f32_16x16x32_bf16 v[8:11], v[174:177], v[236:239], v[8:11]
	v_mfma_f32_16x16x32_bf16 v[4:7], v[204:207], v[236:239], v[4:7]
	s_setprio 3
	s_barrier
	s_add_i32 s63, s63, 2
	s_add_u32 s61, s61, 0x100
	s_addc_u32 s62, s62, 0
	s_cmpk_gt_u32 s63, 0x53
	s_mov_b64 s[34:35], s[36:37]
	s_cbranch_scc0 .LBB0_575
	s_and_b64 vcc, exec, s[28:29]
	s_cbranch_vccz .LBB0_578
	s_barrier

; #define PG8_STAGE(bufoff, gbase, voff) do { _Pragma("unroll") for (int _i = 0; _i < 2; ++_i) \
;         __builtin_amdgcn_global_load_lds((const unsigned*)((const char*)(gbase) + (voff)[_i]), (PG8_LAS unsigned*)(lds + (bufoff) + ldsw + _i * 8192), 16, 0, 0); } while (0)
; #define PG8_LDA(dst, b, h) do { _Pragma("unroll") for (int m = 0; m < 4; ++m) _Pragma("unroll") for (int k = 0; k < 2; ++k) dst[m][k] = *(const PG8_LAS bf16x8*)(lds + PG8_SA(b, h) + aoff + m * 2048 + k * 1024); } while (0)
; #define PG8_LDB(dst, b, h) do { _Pragma("unroll") for (int n = 0; n < 2; ++n) _Pragma("unroll") for (int k = 0; k < 2; ++k) dst[n][k] = *(const PG8_LAS bf16x8*)(lds + PG8_SB(b, h) + boff + n * 2048 + k * 1024); } while (0)
; #define PG8_MMA(ai, bj, At, Bt) do { __builtin_amdgcn_s_setprio(1); _Pragma("unroll") for (int m = 0; m < 4; ++m) _Pragma("unroll") for (int n = 0; n < 2; ++n) _Pragma("unroll") for (int k = 0; k < 2; ++k) \
;         acc[ai][bj][m][n] = __builtin_amdgcn_mfma_f32_16x16x32_bf16(Bt[n][k], At[m][k], acc[ai][bj][m][n], 0, 0, 0); __builtin_amdgcn_s_setprio(0); } while (0)
; #define PG8_WAIT_V(n) asm volatile("s_waitcnt vmcnt(" #n ")" ::: "memory")
; #define PG8_WAIT_L(n) asm volatile("s_waitcnt lgkmcnt(" #n ")" ::: "memory")
; template <class Epi, class Sched, bool ALIGN_EPI = false, bool SP2 = false>
; __device__ __forceinline__ void gemm_phase(PG8_LAS unsigned char* lds, const Gemm g, const Sched& S, const Epi& E) {
;     ...
;             const bool last = (t == nt - 2);
;             const char* a1 = cA + (size_t)(t + 1) * kstep;
;             const char* a2 = last ? nA : cA + (size_t)(t + 2) * kstep; const char* b2 = last ? nB : cB + (size_t)(t + 2) * kstep;
;             const char* a3 = a2 + kstep; const char* b3 = b2 + kstep;
;             if (last && has_next) S.a_ready(nxt);
;             if constexpr (SP2) {
;             PG8_LDB(B0, 0, 0); PG8_LDB(B1, 0, 1); PG8_SCHED; PG8_LDA(At, 0, 0); PG8_STAGE(PG8_SA(1, 1), a1 + hstep, voffA);
;             PG8_WAIT_V(8); PG8_WAIT_L(0); PG8_BAR; PG8_MMA(0, 0, At, B0); PG8_MMA(0, 1, At, B1); PG8_BAR; PG8_SCHED;
;             PG8_LDA(At, 0, 1); PG8_STAGE(PG8_SB(0, 0), b2, voffB); PG8_STAGE(PG8_SB(0, 1), b2 + hstep, voffB); PG8_STAGE(PG8_SA(0, 0), a2, voffA);
;             PG8_WAIT_V(8); PG8_WAIT_L(0); PG8_BAR; PG8_MMA(1, 0, At, B0); PG8_MMA(1, 1, At, B1); PG8_BAR; PG8_SCHED;
.LBB0_674:
	s_add_u32 s42, s40, 0xfff80080
	s_addc_u32 s43, s41, -1
	s_add_i32 s64, 0, 0x10000
	s_cmp_eq_u32 s63, 28
	s_cselect_b32 s45, s5, s43
	s_cselect_b32 s44, s4, s42
	s_cselect_b32 s43, s37, s62
	s_cselect_b32 s42, s36, s35
	s_add_i32 s66, 0, 0x14000
	v_add_u32_e32 v144, s64, v173
	v_add_u32_e32 v162, s66, v173
	ds_read_b128 v[132:135], v144
	ds_read_b128 v[136:139], v144 offset:1024
	ds_read_b128 v[140:143], v144 offset:2048
	ds_read_b128 v[144:147], v144 offset:3072
	ds_read_b128 v[158:161], v162
	ds_read_b128 v[174:177], v162 offset:1024
	ds_read_b128 v[206:209], v162 offset:2048
	ds_read_b128 v[210:213], v162 offset:3072
	s_add_i32 m0, s39, 0xc000
	ds_read_b128 v[214:217], v204
	ds_read_b128 v[218:221], v204 offset:1024
	ds_read_b128 v[222:225], v204 offset:2048
	ds_read_b128 v[226:229], v204 offset:3072
	ds_read_b128 v[230:233], v204 offset:4096
	ds_read_b128 v[234:237], v204 offset:5120
	ds_read_b128 v[238:241], v204 offset:6144
	ds_read_b128 v[242:245], v204 offset:7168
	global_load_lds_dwordx4 v154, s[40:41]
	s_add_i32 m0, s39, 0xe000
	s_nop 0
	global_load_lds_dwordx4 v156, s[40:41]
	s_waitcnt vmcnt(8)
	s_waitcnt lgkmcnt(0)
	s_barrier
	s_setprio 0
	s_waitcnt lgkmcnt(0)
	v_mfma_f32_16x16x32_bf16 v[128:131], v[132:135], v[214:217], v[128:131]
	v_mfma_f32_16x16x32_bf16 v[124:127], v[140:143], v[214:217], v[124:127]
	v_mfma_f32_16x16x32_bf16 v[116:119], v[132:135], v[222:225], v[116:119]
	v_mfma_f32_16x16x32_bf16 v[108:111], v[140:143], v[222:225], v[108:111]
	v_mfma_f32_16x16x32_bf16 v[100:103], v[132:135], v[230:233], v[100:103]
	v_mfma_f32_16x16x32_bf16 v[92:95], v[140:143], v[230:233], v[92:95]
	v_mfma_f32_16x16x32_bf16 v[84:87], v[132:135], v[238:241], v[84:87]
	v_mfma_f32_16x16x32_bf16 v[76:79], v[140:143], v[238:241], v[76:79]
	v_mfma_f32_16x16x32_bf16 v[128:131], v[136:139], v[218:221], v[128:131]
	v_mfma_f32_16x16x32_bf16 v[124:127], v[144:147], v[218:221], v[124:127]
	v_mfma_f32_16x16x32_bf16 v[116:119], v[136:139], v[226:229], v[116:119]
	v_mfma_f32_16x16x32_bf16 v[108:111], v[144:147], v[226:229], v[108:111]
	v_mfma_f32_16x16x32_bf16 v[100:103], v[136:139], v[234:237], v[100:103]
	v_mfma_f32_16x16x32_bf16 v[92:95], v[144:147], v[234:237], v[92:95]
	v_mfma_f32_16x16x32_bf16 v[84:87], v[136:139], v[242:245], v[84:87]
	v_mfma_f32_16x16x32_bf16 v[76:79], v[144:147], v[242:245], v[76:79]
	v_mfma_f32_16x16x32_bf16 v[120:123], v[158:161], v[214:217], v[120:123]
	v_mfma_f32_16x16x32_bf16 v[112:115], v[206:209], v[214:217], v[112:115]
	v_mfma_f32_16x16x32_bf16 v[104:107], v[158:161], v[222:225], v[104:107]
	v_mfma_f32_16x16x32_bf16 v[96:99], v[206:209], v[222:225], v[96:99]
	v_mfma_f32_16x16x32_bf16 v[88:91], v[158:161], v[230:233], v[88:91]
	v_mfma_f32_16x16x32_bf16 v[80:83], v[206:209], v[230:233], v[80:83]
	v_mfma_f32_16x16x32_bf16 v[72:75], v[158:161], v[238:241], v[72:75]
	v_mfma_f32_16x16x32_bf16 v[68:71], v[206:209], v[238:241], v[68:71]
	v_mfma_f32_16x16x32_bf16 v[120:123], v[174:177], v[218:221], v[120:123]
	v_mfma_f32_16x16x32_bf16 v[112:115], v[210:213], v[218:221], v[112:115]
	v_mfma_f32_16x16x32_bf16 v[104:107], v[174:177], v[226:229], v[104:107]
	v_mfma_f32_16x16x32_bf16 v[96:99], v[210:213], v[226:229], v[96:99]
	v_mfma_f32_16x16x32_bf16 v[88:91], v[174:177], v[234:237], v[88:91]
	v_mfma_f32_16x16x32_bf16 v[80:83], v[210:213], v[234:237], v[80:83]
	v_mfma_f32_16x16x32_bf16 v[72:75], v[174:177], v[242:245], v[72:75]
	v_mfma_f32_16x16x32_bf16 v[68:71], v[210:213], v[242:245], v[68:71]
	s_setprio 3
	s_barrier
	s_add_i32 s64, s64, s46
	s_mov_b32 m0, s64
	ds_read_b128 v[214:217], v204 offset:16384
	ds_read_b128 v[218:221], v204 offset:17408
	ds_read_b128 v[222:225], v204 offset:18432
	ds_read_b128 v[226:229], v204 offset:19456
	ds_read_b128 v[230:233], v204 offset:20480
	ds_read_b128 v[234:237], v204 offset:21504
	ds_read_b128 v[238:241], v204 offset:22528
	ds_read_b128 v[242:245], v204 offset:23552
	global_load_lds_dwordx4 v2, s[42:43]
	s_add_i32 m0, s64, 0x2000
	s_add_u32 s64, s42, 0x80000
	s_addc_u32 s65, s43, 0
	s_add_i32 s66, s66, s46
	global_load_lds_dwordx4 v148, s[42:43]
	s_mov_b32 m0, s66
	s_nop 0
	global_load_lds_dwordx4 v2, s[64:65]
	s_add_i32 m0, s66, 0x2000
	s_nop 0
	global_load_lds_dwordx4 v148, s[64:65]
	s_mov_b32 m0, s39
	s_nop 0
	global_load_lds_dwordx4 v152, s[44:45]
	s_mov_b32 m0, s51
	s_nop 0
	global_load_lds_dwordx4 v150, s[44:45]
	s_waitcnt vmcnt(8)
	s_waitcnt lgkmcnt(0)
	s_barrier
	s_setprio 0
	s_waitcnt lgkmcnt(0)
	v_mfma_f32_16x16x32_bf16 v[64:67], v[132:135], v[214:217], v[64:67]
	v_mfma_f32_16x16x32_bf16 v[60:63], v[140:143], v[214:217], v[60:63]
	v_mfma_f32_16x16x32_bf16 v[52:55], v[132:135], v[222:225], v[52:55]
	v_mfma_f32_16x16x32_bf16 v[44:47], v[140:143], v[222:225], v[44:47]
	v_mfma_f32_16x16x32_bf16 v[36:39], v[132:135], v[230:233], v[36:39]
	v_mfma_f32_16x16x32_bf16 v[28:31], v[140:143], v[230:233], v[28:31]
	v_mfma_f32_16x16x32_bf16 v[20:23], v[132:135], v[238:241], v[20:23]
	v_mfma_f32_16x16x32_bf16 v[12:15], v[140:143], v[238:241], v[12:15]
	v_mfma_f32_16x16x32_bf16 v[64:67], v[136:139], v[218:221], v[64:67]
	v_mfma_f32_16x16x32_bf16 v[60:63], v[144:147], v[218:221], v[60:63]
	v_mfma_f32_16x16x32_bf16 v[52:55], v[136:139], v[226:229], v[52:55]
	v_mfma_f32_16x16x32_bf16 v[44:47], v[144:147], v[226:229], v[44:47]
	v_mfma_f32_16x16x32_bf16 v[36:39], v[136:139], v[234:237], v[36:39]
	v_mfma_f32_16x16x32_bf16 v[28:31], v[144:147], v[234:237], v[28:31]
	v_mfma_f32_16x16x32_bf16 v[20:23], v[136:139], v[242:245], v[20:23]
	v_mfma_f32_16x16x32_bf16 v[12:15], v[144:147], v[242:245], v[12:15]
	v_mfma_f32_16x16x32_bf16 v[56:59], v[158:161], v[214:217], v[56:59]
	v_mfma_f32_16x16x32_bf16 v[48:51], v[206:209], v[214:217], v[48:51]
	v_mfma_f32_16x16x32_bf16 v[40:43], v[158:161], v[222:225], v[40:43]
	v_mfma_f32_16x16x32_bf16 v[32:35], v[206:209], v[222:225], v[32:35]
	v_mfma_f32_16x16x32_bf16 v[24:27], v[158:161], v[230:233], v[24:27]
	v_mfma_f32_16x16x32_bf16 v[16:19], v[206:209], v[230:233], v[16:19]
	v_mfma_f32_16x16x32_bf16 v[8:11], v[158:161], v[238:241], v[8:11]
	v_mfma_f32_16x16x32_bf16 v[4:7], v[206:209], v[238:241], v[4:7]
	v_mfma_f32_16x16x32_bf16 v[56:59], v[174:177], v[218:221], v[56:59]
	v_mfma_f32_16x16x32_bf16 v[48:51], v[210:213], v[218:221], v[48:51]
	v_mfma_f32_16x16x32_bf16 v[40:43], v[174:177], v[226:229], v[40:43]
	v_mfma_f32_16x16x32_bf16 v[32:35], v[210:213], v[226:229], v[32:35]
	v_mfma_f32_16x16x32_bf16 v[24:27], v[174:177], v[234:237], v[24:27]
	v_mfma_f32_16x16x32_bf16 v[16:19], v[210:213], v[234:237], v[16:19]
	v_mfma_f32_16x16x32_bf16 v[8:11], v[174:177], v[242:245], v[8:11]
	v_mfma_f32_16x16x32_bf16 v[4:7], v[210:213], v[242:245], v[4:7]
	s_setprio 3
	s_barrier
; #define PG8_STAGE(bufoff, gbase, voff) do { _Pragma("unroll") for (int _i = 0; _i < 2; ++_i) \
;         __builtin_amdgcn_global_load_lds((const unsigned*)((const char*)(gbase) + (voff)[_i]), (PG8_LAS unsigned*)(lds + (bufoff) + ldsw + _i * 8192), 16, 0, 0); } while (0)
; #define PG8_LDA(dst, b, h) do { _Pragma("unroll") for (int m = 0; m < 4; ++m) _Pragma("unroll") for (int k = 0; k < 2; ++k) dst[m][k] = *(const PG8_LAS bf16x8*)(lds + PG8_SA(b, h) + aoff + m * 2048 + k * 1024); } while (0)
; #define PG8_LDB(dst, b, h) do { _Pragma("unroll") for (int n = 0; n < 2; ++n) _Pragma("unroll") for (int k = 0; k < 2; ++k) dst[n][k] = *(const PG8_LAS bf16x8*)(lds + PG8_SB(b, h) + boff + n * 2048 + k * 1024); } while (0)
; #define PG8_MMA(ai, bj, At, Bt) do { __builtin_amdgcn_s_setprio(1); _Pragma("unroll") for (int m = 0; m < 4; ++m) _Pragma("unroll") for (int n = 0; n < 2; ++n) _Pragma("unroll") for (int k = 0; k < 2; ++k) \
;         acc[ai][bj][m][n] = __builtin_amdgcn_mfma_f32_16x16x32_bf16(Bt[n][k], At[m][k], acc[ai][bj][m][n], 0, 0, 0); __builtin_amdgcn_s_setprio(0); } while (0)
; #define PG8_WAIT_V(n) asm volatile("s_waitcnt vmcnt(" #n ")" ::: "memory")
; #define PG8_WAIT_L(n) asm volatile("s_waitcnt lgkmcnt(" #n ")" ::: "memory")
; #define PG8_BAR __builtin_amdgcn_s_barrier()
; #define PG8_SCHED __builtin_amdgcn_sched_barrier(0)
; template <class Epi, class Sched, bool ALIGN_EPI = false, bool SP2 = false>
; __device__ __forceinline__ void gemm_phase(PG8_LAS unsigned char* lds, const Gemm g, const Sched& S, const Epi& E) {
;     ...
;             PG8_LDB(B0, 1, 0); PG8_LDB(B1, 1, 1); PG8_SCHED; PG8_LDA(At, 1, 0); PG8_STAGE(PG8_SA(0, 1), a2 + hstep, voffA);
;             PG8_WAIT_V(8); PG8_WAIT_L(0); PG8_BAR; PG8_MMA(0, 0, At, B0); PG8_MMA(0, 1, At, B1); PG8_BAR; PG8_SCHED;
;             PG8_LDA(At, 1, 1); PG8_STAGE(PG8_SB(1, 0), b3, voffB); PG8_STAGE(PG8_SB(1, 1), b3 + hstep, voffB); PG8_STAGE(PG8_SA(1, 0), a3, voffA);
;             PG8_WAIT_V(8); PG8_WAIT_L(0); PG8_BAR; PG8_MMA(1, 0, At, B0); PG8_MMA(1, 1, At, B1); PG8_BAR; PG8_SCHED;
	s_add_i32 s64, 0, 0x18000
	s_add_i32 s65, 0, 0x1c000
	v_add_u32_e32 v144, s64, v173
	v_add_u32_e32 v164, s65, v173
	ds_read_b128 v[132:135], v144
	ds_read_b128 v[136:139], v144 offset:1024
	ds_read_b128 v[140:143], v144 offset:2048
	ds_read_b128 v[144:147], v144 offset:3072
	ds_read_b128 v[158:161], v164
	ds_read_b128 v[174:177], v164 offset:1024
	ds_read_b128 v[206:209], v164 offset:2048
	ds_read_b128 v[210:213], v164 offset:3072
	s_add_u32 s100, s44, 0x80
	s_addc_u32 s101, s45, 0
	s_add_u32 s44, s44, 0x80000
	s_addc_u32 s45, s45, 0
	s_mov_b32 m0, s52
	ds_read_b128 v[214:217], v204 offset:32768
	ds_read_b128 v[218:221], v204 offset:33792
	ds_read_b128 v[222:225], v204 offset:34816
	ds_read_b128 v[226:229], v204 offset:35840
	ds_read_b128 v[230:233], v204 offset:36864
	ds_read_b128 v[234:237], v204 offset:37888
	ds_read_b128 v[238:241], v204 offset:38912
	ds_read_b128 v[242:245], v204 offset:39936
	global_load_lds_dwordx4 v152, s[44:45]
	s_mov_b32 m0, s53
	s_nop 0
	global_load_lds_dwordx4 v150, s[44:45]
	s_waitcnt vmcnt(8)
	s_waitcnt lgkmcnt(0)
	s_barrier
	s_setprio 0
	s_waitcnt lgkmcnt(0)
	v_mfma_f32_16x16x32_bf16 v[128:131], v[132:135], v[214:217], v[128:131]
	v_mfma_f32_16x16x32_bf16 v[124:127], v[140:143], v[214:217], v[124:127]
	v_mfma_f32_16x16x32_bf16 v[116:119], v[132:135], v[222:225], v[116:119]
	v_mfma_f32_16x16x32_bf16 v[108:111], v[140:143], v[222:225], v[108:111]
	v_mfma_f32_16x16x32_bf16 v[100:103], v[132:135], v[230:233], v[100:103]
	v_mfma_f32_16x16x32_bf16 v[92:95], v[140:143], v[230:233], v[92:95]
	v_mfma_f32_16x16x32_bf16 v[84:87], v[132:135], v[238:241], v[84:87]
	v_mfma_f32_16x16x32_bf16 v[76:79], v[140:143], v[238:241], v[76:79]
	v_mfma_f32_16x16x32_bf16 v[128:131], v[136:139], v[218:221], v[128:131]
	v_mfma_f32_16x16x32_bf16 v[124:127], v[144:147], v[218:221], v[124:127]
	v_mfma_f32_16x16x32_bf16 v[116:119], v[136:139], v[226:229], v[116:119]
	v_mfma_f32_16x16x32_bf16 v[108:111], v[144:147], v[226:229], v[108:111]
	v_mfma_f32_16x16x32_bf16 v[100:103], v[136:139], v[234:237], v[100:103]
	v_mfma_f32_16x16x32_bf16 v[92:95], v[144:147], v[234:237], v[92:95]
	v_mfma_f32_16x16x32_bf16 v[84:87], v[136:139], v[242:245], v[84:87]
	v_mfma_f32_16x16x32_bf16 v[76:79], v[144:147], v[242:245], v[76:79]
	v_mfma_f32_16x16x32_bf16 v[120:123], v[158:161], v[214:217], v[120:123]
	v_mfma_f32_16x16x32_bf16 v[112:115], v[206:209], v[214:217], v[112:115]
	v_mfma_f32_16x16x32_bf16 v[104:107], v[158:161], v[222:225], v[104:107]
	v_mfma_f32_16x16x32_bf16 v[96:99], v[206:209], v[222:225], v[96:99]
	v_mfma_f32_16x16x32_bf16 v[88:91], v[158:161], v[230:233], v[88:91]
	v_mfma_f32_16x16x32_bf16 v[80:83], v[206:209], v[230:233], v[80:83]
	v_mfma_f32_16x16x32_bf16 v[72:75], v[158:161], v[238:241], v[72:75]
	v_mfma_f32_16x16x32_bf16 v[68:71], v[206:209], v[238:241], v[68:71]
	v_mfma_f32_16x16x32_bf16 v[120:123], v[174:177], v[218:221], v[120:123]
	v_mfma_f32_16x16x32_bf16 v[112:115], v[210:213], v[218:221], v[112:115]
	v_mfma_f32_16x16x32_bf16 v[104:107], v[174:177], v[226:229], v[104:107]
	v_mfma_f32_16x16x32_bf16 v[96:99], v[210:213], v[226:229], v[96:99]
	v_mfma_f32_16x16x32_bf16 v[88:91], v[174:177], v[234:237], v[88:91]
	v_mfma_f32_16x16x32_bf16 v[80:83], v[210:213], v[234:237], v[80:83]
	v_mfma_f32_16x16x32_bf16 v[72:75], v[174:177], v[242:245], v[72:75]
	v_mfma_f32_16x16x32_bf16 v[68:71], v[210:213], v[242:245], v[68:71]
	s_setprio 3
	s_barrier
	s_add_i32 s44, s64, s46
	s_add_i32 m0, s44, 0xffffff80
	ds_read_b128 v[214:217], v204 offset:49152
	ds_read_b128 v[218:221], v204 offset:50176
	ds_read_b128 v[222:225], v204 offset:51200
	ds_read_b128 v[226:229], v204 offset:52224
	ds_read_b128 v[230:233], v204 offset:53248
	ds_read_b128 v[234:237], v204 offset:54272
	ds_read_b128 v[238:241], v204 offset:55296
	ds_read_b128 v[242:245], v204 offset:56320
	global_load_lds_dwordx4 v2, s[42:43] offset:128
	s_add_i32 m0, s44, 0x1f80
	s_add_i32 s44, s65, s46
	global_load_lds_dwordx4 v148, s[42:43] offset:128
	s_add_u32 s42, s42, 0x80080
	s_addc_u32 s43, s43, 0
	s_mov_b32 m0, s44
	s_nop 0
	global_load_lds_dwordx4 v2, s[42:43]
	s_add_i32 m0, s44, 0x2000
	s_nop 0
	global_load_lds_dwordx4 v148, s[42:43]
	s_mov_b32 m0, s54
	s_nop 0
	global_load_lds_dwordx4 v152, s[100:101]
	s_mov_b32 m0, s55
	s_nop 0
	global_load_lds_dwordx4 v150, s[100:101]
	s_nop 0
	s_waitcnt vmcnt(8)
	s_waitcnt lgkmcnt(0)
	s_barrier
	s_setprio 0
	s_waitcnt lgkmcnt(0)
	v_mfma_f32_16x16x32_bf16 v[64:67], v[132:135], v[214:217], v[64:67]
	v_mfma_f32_16x16x32_bf16 v[60:63], v[140:143], v[214:217], v[60:63]
	v_mfma_f32_16x16x32_bf16 v[52:55], v[132:135], v[222:225], v[52:55]
	v_mfma_f32_16x16x32_bf16 v[44:47], v[140:143], v[222:225], v[44:47]
	v_mfma_f32_16x16x32_bf16 v[36:39], v[132:135], v[230:233], v[36:39]
	v_mfma_f32_16x16x32_bf16 v[28:31], v[140:143], v[230:233], v[28:31]
	v_mfma_f32_16x16x32_bf16 v[20:23], v[132:135], v[238:241], v[20:23]
	v_mfma_f32_16x16x32_bf16 v[12:15], v[140:143], v[238:241], v[12:15]
	v_mfma_f32_16x16x32_bf16 v[64:67], v[136:139], v[218:221], v[64:67]
	v_mfma_f32_16x16x32_bf16 v[60:63], v[144:147], v[218:221], v[60:63]
	v_mfma_f32_16x16x32_bf16 v[52:55], v[136:139], v[226:229], v[52:55]
	v_mfma_f32_16x16x32_bf16 v[44:47], v[144:147], v[226:229], v[44:47]
	v_mfma_f32_16x16x32_bf16 v[36:39], v[136:139], v[234:237], v[36:39]
	v_mfma_f32_16x16x32_bf16 v[28:31], v[144:147], v[234:237], v[28:31]
	v_mfma_f32_16x16x32_bf16 v[20:23], v[136:139], v[242:245], v[20:23]
	v_mfma_f32_16x16x32_bf16 v[12:15], v[144:147], v[242:245], v[12:15]
	v_mfma_f32_16x16x32_bf16 v[56:59], v[158:161], v[214:217], v[56:59]
	v_mfma_f32_16x16x32_bf16 v[48:51], v[206:209], v[214:217], v[48:51]
	v_mfma_f32_16x16x32_bf16 v[40:43], v[158:161], v[222:225], v[40:43]
	v_mfma_f32_16x16x32_bf16 v[32:35], v[206:209], v[222:225], v[32:35]
	v_mfma_f32_16x16x32_bf16 v[24:27], v[158:161], v[230:233], v[24:27]
	v_mfma_f32_16x16x32_bf16 v[16:19], v[206:209], v[230:233], v[16:19]
	v_mfma_f32_16x16x32_bf16 v[8:11], v[158:161], v[238:241], v[8:11]
	v_mfma_f32_16x16x32_bf16 v[4:7], v[206:209], v[238:241], v[4:7]
	v_mfma_f32_16x16x32_bf16 v[56:59], v[174:177], v[218:221], v[56:59]
	v_mfma_f32_16x16x32_bf16 v[48:51], v[210:213], v[218:221], v[48:51]
	v_mfma_f32_16x16x32_bf16 v[40:43], v[174:177], v[226:229], v[40:43]
	v_mfma_f32_16x16x32_bf16 v[32:35], v[210:213], v[226:229], v[32:35]
	v_mfma_f32_16x16x32_bf16 v[24:27], v[174:177], v[234:237], v[24:27]
	v_mfma_f32_16x16x32_bf16 v[16:19], v[210:213], v[234:237], v[16:19]
	v_mfma_f32_16x16x32_bf16 v[8:11], v[174:177], v[242:245], v[8:11]
	v_mfma_f32_16x16x32_bf16 v[4:7], v[210:213], v[242:245], v[4:7]
	s_setprio 3
	s_barrier
	s_add_i32 s63, s63, 2
	s_add_u32 s40, s40, 0x100
	s_addc_u32 s41, s41, 0
	s_add_u32 s35, s35, 0x100
	s_addc_u32 s62, s62, 0
	s_cmp_gt_u32 s63, 29
	s_cbranch_scc0 .LBB0_674
	s_and_b64 vcc, exec, s[30:31]
	s_cbranch_vccz .LBB0_677
	s_barrier

; #define PG8_STAGE(bufoff, gbase, voff) do { _Pragma("unroll") for (int _i = 0; _i < 2; ++_i) \
;         __builtin_amdgcn_global_load_lds((const unsigned*)((const char*)(gbase) + (voff)[_i]), (PG8_LAS unsigned*)(lds + (bufoff) + ldsw + _i * 8192), 16, 0, 0); } while (0)
; #define PG8_LDA(dst, b, h) do { _Pragma("unroll") for (int m = 0; m < 4; ++m) _Pragma("unroll") for (int k = 0; k < 2; ++k) dst[m][k] = *(const PG8_LAS bf16x8*)(lds + PG8_SA(b, h) + aoff + m * 2048 + k * 1024); } while (0)
; #define PG8_LDB(dst, b, h) do { _Pragma("unroll") for (int n = 0; n < 2; ++n) _Pragma("unroll") for (int k = 0; k < 2; ++k) dst[n][k] = *(const PG8_LAS bf16x8*)(lds + PG8_SB(b, h) + boff + n * 2048 + k * 1024); } while (0)
; #define PG8_MMA(ai, bj, At, Bt) do { __builtin_amdgcn_s_setprio(1); _Pragma("unroll") for (int m = 0; m < 4; ++m) _Pragma("unroll") for (int n = 0; n < 2; ++n) _Pragma("unroll") for (int k = 0; k < 2; ++k) \
;         acc[ai][bj][m][n] = __builtin_amdgcn_mfma_f32_16x16x32_bf16(Bt[n][k], At[m][k], acc[ai][bj][m][n], 0, 0, 0); __builtin_amdgcn_s_setprio(0); } while (0)
; #define PG8_WAIT_V(n) asm volatile("s_waitcnt vmcnt(" #n ")" ::: "memory")
; #define PG8_WAIT_L(n) asm volatile("s_waitcnt lgkmcnt(" #n ")" ::: "memory")
; template <class Epi, class Sched, bool ALIGN_EPI = false, bool SP2 = false>
; __device__ __forceinline__ void gemm_phase(PG8_LAS unsigned char* lds, const Gemm g, const Sched& S, const Epi& E) {
;     ...
;             const bool last = (t == nt - 2);
;             const char* a1 = cA + (size_t)(t + 1) * kstep;
;             const char* a2 = last ? nA : cA + (size_t)(t + 2) * kstep; const char* b2 = last ? nB : cB + (size_t)(t + 2) * kstep;
;             const char* a3 = a2 + kstep; const char* b3 = b2 + kstep;
;             if (last && has_next) S.a_ready(nxt);
;             if constexpr (SP2) {
;             PG8_LDB(B0, 0, 0); PG8_LDB(B1, 0, 1); PG8_SCHED; PG8_LDA(At, 0, 0); PG8_STAGE(PG8_SA(1, 1), a1 + hstep, voffA);
;             PG8_WAIT_V(8); PG8_WAIT_L(0); PG8_BAR; PG8_MMA(0, 0, At, B0); PG8_MMA(0, 1, At, B1); PG8_BAR; PG8_SCHED;
;             PG8_LDA(At, 0, 1); PG8_STAGE(PG8_SB(0, 0), b2, voffB); PG8_STAGE(PG8_SB(0, 1), b2 + hstep, voffB); PG8_STAGE(PG8_SA(0, 0), a2, voffA);
;             PG8_WAIT_V(8); PG8_WAIT_L(0); PG8_BAR; PG8_MMA(1, 0, At, B0); PG8_MMA(1, 1, At, B1); PG8_BAR; PG8_SCHED;
.LBB0_2096:
	s_add_u32 s27, s40, 0xfffc0080
	s_addc_u32 s29, s41, -1
	s_add_i32 s31, 0, 0x10000
	s_cmp_eq_u32 s26, 12
	s_cselect_b32 s45, s1, s29
	s_cselect_b32 s44, s0, s27
	v_add_u32_e32 v2, s31, v173
	s_cselect_b32 s43, s35, s13
	s_cselect_b32 s42, s34, s11
	s_add_i32 s27, 0, 0x14000
	ds_read_b128 v[134:137], v2
	ds_read_b128 v[138:141], v2 offset:1024
	ds_read_b128 v[154:157], v2 offset:2048
	ds_read_b128 v[158:161], v2 offset:3072
	v_add_u32_e32 v2, s27, v173
	ds_read_b128 v[178:181], v2
	ds_read_b128 v[204:207], v2 offset:1024
	ds_read_b128 v[208:211], v2 offset:2048
	ds_read_b128 v[212:215], v2 offset:3072
	s_add_i32 m0, s55, 0xc000
	ds_read_b128 v[216:219], v177
	ds_read_b128 v[220:223], v177 offset:1024
	ds_read_b128 v[224:227], v177 offset:2048
	ds_read_b128 v[228:231], v177 offset:3072
	ds_read_b128 v[232:235], v177 offset:4096
	ds_read_b128 v[236:239], v177 offset:5120
	ds_read_b128 v[240:243], v177 offset:6144
	ds_read_b128 v[244:247], v177 offset:7168
	global_load_lds_dwordx4 v150, s[40:41]
	s_add_i32 m0, s55, 0xe000
	s_nop 0
	global_load_lds_dwordx4 v152, s[40:41]
	s_waitcnt vmcnt(8)
	s_waitcnt lgkmcnt(0)
	s_barrier
	s_setprio 0
	s_waitcnt lgkmcnt(0)
	v_mfma_f32_16x16x32_bf16 v[130:133], v[134:137], v[216:219], v[130:133]
	v_mfma_f32_16x16x32_bf16 v[126:129], v[154:157], v[216:219], v[126:129]
	v_mfma_f32_16x16x32_bf16 v[122:125], v[134:137], v[224:227], v[122:125]
	v_mfma_f32_16x16x32_bf16 v[118:121], v[154:157], v[224:227], v[118:121]
	v_mfma_f32_16x16x32_bf16 v[114:117], v[134:137], v[232:235], v[114:117]
	v_mfma_f32_16x16x32_bf16 v[110:113], v[154:157], v[232:235], v[110:113]
	v_mfma_f32_16x16x32_bf16 v[106:109], v[134:137], v[240:243], v[106:109]
	v_mfma_f32_16x16x32_bf16 v[102:105], v[154:157], v[240:243], v[102:105]
	v_mfma_f32_16x16x32_bf16 v[130:133], v[138:141], v[220:223], v[130:133]
	v_mfma_f32_16x16x32_bf16 v[126:129], v[158:161], v[220:223], v[126:129]
	v_mfma_f32_16x16x32_bf16 v[122:125], v[138:141], v[228:231], v[122:125]
	v_mfma_f32_16x16x32_bf16 v[118:121], v[158:161], v[228:231], v[118:121]
	v_mfma_f32_16x16x32_bf16 v[114:117], v[138:141], v[236:239], v[114:117]
	v_mfma_f32_16x16x32_bf16 v[110:113], v[158:161], v[236:239], v[110:113]
	v_mfma_f32_16x16x32_bf16 v[106:109], v[138:141], v[244:247], v[106:109]
	v_mfma_f32_16x16x32_bf16 v[102:105], v[158:161], v[244:247], v[102:105]
	v_mfma_f32_16x16x32_bf16 v[98:101], v[178:181], v[216:219], v[98:101]
	v_mfma_f32_16x16x32_bf16 v[94:97], v[208:211], v[216:219], v[94:97]
	v_mfma_f32_16x16x32_bf16 v[90:93], v[178:181], v[224:227], v[90:93]
	v_mfma_f32_16x16x32_bf16 v[86:89], v[208:211], v[224:227], v[86:89]
	v_mfma_f32_16x16x32_bf16 v[82:85], v[178:181], v[232:235], v[82:85]
	v_mfma_f32_16x16x32_bf16 v[78:81], v[208:211], v[232:235], v[78:81]
	v_mfma_f32_16x16x32_bf16 v[74:77], v[178:181], v[240:243], v[74:77]
	v_mfma_f32_16x16x32_bf16 v[70:73], v[208:211], v[240:243], v[70:73]
	v_mfma_f32_16x16x32_bf16 v[98:101], v[204:207], v[220:223], v[98:101]
	v_mfma_f32_16x16x32_bf16 v[94:97], v[212:215], v[220:223], v[94:97]
	v_mfma_f32_16x16x32_bf16 v[90:93], v[204:207], v[228:231], v[90:93]
	v_mfma_f32_16x16x32_bf16 v[86:89], v[212:215], v[228:231], v[86:89]
	v_mfma_f32_16x16x32_bf16 v[82:85], v[204:207], v[236:239], v[82:85]
	v_mfma_f32_16x16x32_bf16 v[78:81], v[212:215], v[236:239], v[78:81]
	v_mfma_f32_16x16x32_bf16 v[74:77], v[204:207], v[244:247], v[74:77]
	v_mfma_f32_16x16x32_bf16 v[70:73], v[212:215], v[244:247], v[70:73]
	s_setprio 3
	s_barrier
	s_add_i32 s29, s31, s54
	s_mov_b32 m0, s29
	ds_read_b128 v[216:219], v177 offset:16384
	ds_read_b128 v[220:223], v177 offset:17408
	ds_read_b128 v[224:227], v177 offset:18432
	ds_read_b128 v[228:231], v177 offset:19456
	ds_read_b128 v[232:235], v177 offset:20480
	ds_read_b128 v[236:239], v177 offset:21504
	ds_read_b128 v[240:243], v177 offset:22528
	ds_read_b128 v[244:247], v177 offset:23552
	global_load_lds_dwordx4 v144, s[42:43]
	s_add_i32 m0, s29, 0x2000
	s_add_u32 s64, s42, 0x40000
	s_addc_u32 s65, s43, 0
	s_add_i32 s27, s27, s54
	global_load_lds_dwordx4 v148, s[42:43]
	s_mov_b32 m0, s27
	s_nop 0
	global_load_lds_dwordx4 v144, s[64:65]
	s_add_i32 m0, s27, 0x2000
	s_nop 0
	global_load_lds_dwordx4 v148, s[64:65]
	s_mov_b32 m0, s55
	s_nop 0
	global_load_lds_dwordx4 v142, s[44:45]
	s_mov_b32 m0, s56
	s_nop 0
	global_load_lds_dwordx4 v146, s[44:45]
	s_waitcnt vmcnt(8)
	s_waitcnt lgkmcnt(0)
	s_barrier
	s_setprio 0
	s_waitcnt lgkmcnt(0)
	v_mfma_f32_16x16x32_bf16 v[66:69], v[134:137], v[216:219], v[66:69]
	v_mfma_f32_16x16x32_bf16 v[62:65], v[154:157], v[216:219], v[62:65]
	v_mfma_f32_16x16x32_bf16 v[58:61], v[134:137], v[224:227], v[58:61]
	v_mfma_f32_16x16x32_bf16 v[54:57], v[154:157], v[224:227], v[54:57]
	v_mfma_f32_16x16x32_bf16 v[50:53], v[134:137], v[232:235], v[50:53]
	v_mfma_f32_16x16x32_bf16 v[46:49], v[154:157], v[232:235], v[46:49]
	v_mfma_f32_16x16x32_bf16 v[42:45], v[134:137], v[240:243], v[42:45]
	v_mfma_f32_16x16x32_bf16 v[38:41], v[154:157], v[240:243], v[38:41]
	v_mfma_f32_16x16x32_bf16 v[66:69], v[138:141], v[220:223], v[66:69]
	v_mfma_f32_16x16x32_bf16 v[62:65], v[158:161], v[220:223], v[62:65]
	v_mfma_f32_16x16x32_bf16 v[58:61], v[138:141], v[228:231], v[58:61]
	v_mfma_f32_16x16x32_bf16 v[54:57], v[158:161], v[228:231], v[54:57]
	v_mfma_f32_16x16x32_bf16 v[50:53], v[138:141], v[236:239], v[50:53]
	v_mfma_f32_16x16x32_bf16 v[46:49], v[158:161], v[236:239], v[46:49]
	v_mfma_f32_16x16x32_bf16 v[42:45], v[138:141], v[244:247], v[42:45]
	v_mfma_f32_16x16x32_bf16 v[38:41], v[158:161], v[244:247], v[38:41]
	v_mfma_f32_16x16x32_bf16 v[34:37], v[178:181], v[216:219], v[34:37]
	v_mfma_f32_16x16x32_bf16 v[30:33], v[208:211], v[216:219], v[30:33]
	v_mfma_f32_16x16x32_bf16 v[26:29], v[178:181], v[224:227], v[26:29]
	v_mfma_f32_16x16x32_bf16 v[22:25], v[208:211], v[224:227], v[22:25]
	v_mfma_f32_16x16x32_bf16 v[18:21], v[178:181], v[232:235], v[18:21]
	v_mfma_f32_16x16x32_bf16 v[14:17], v[208:211], v[232:235], v[14:17]
	v_mfma_f32_16x16x32_bf16 v[10:13], v[178:181], v[240:243], v[10:13]
	v_mfma_f32_16x16x32_bf16 v[4:7], v[208:211], v[240:243], v[6:9]
	v_mfma_f32_16x16x32_bf16 v[34:37], v[204:207], v[220:223], v[34:37]
	v_mfma_f32_16x16x32_bf16 v[30:33], v[212:215], v[220:223], v[30:33]
	v_mfma_f32_16x16x32_bf16 v[26:29], v[204:207], v[228:231], v[26:29]
	v_mfma_f32_16x16x32_bf16 v[22:25], v[212:215], v[228:231], v[22:25]
	v_mfma_f32_16x16x32_bf16 v[18:21], v[204:207], v[236:239], v[18:21]
	v_mfma_f32_16x16x32_bf16 v[14:17], v[212:215], v[236:239], v[14:17]
	v_mfma_f32_16x16x32_bf16 v[10:13], v[204:207], v[244:247], v[10:13]
	v_mfma_f32_16x16x32_bf16 v[4:7], v[212:215], v[244:247], v[4:7]
	s_setprio 3
	s_barrier
; #define PG8_STAGE(bufoff, gbase, voff) do { _Pragma("unroll") for (int _i = 0; _i < 2; ++_i) \
;         __builtin_amdgcn_global_load_lds((const unsigned*)((const char*)(gbase) + (voff)[_i]), (PG8_LAS unsigned*)(lds + (bufoff) + ldsw + _i * 8192), 16, 0, 0); } while (0)
; #define PG8_LDA(dst, b, h) do { _Pragma("unroll") for (int m = 0; m < 4; ++m) _Pragma("unroll") for (int k = 0; k < 2; ++k) dst[m][k] = *(const PG8_LAS bf16x8*)(lds + PG8_SA(b, h) + aoff + m * 2048 + k * 1024); } while (0)
; #define PG8_LDB(dst, b, h) do { _Pragma("unroll") for (int n = 0; n < 2; ++n) _Pragma("unroll") for (int k = 0; k < 2; ++k) dst[n][k] = *(const PG8_LAS bf16x8*)(lds + PG8_SB(b, h) + boff + n * 2048 + k * 1024); } while (0)
; #define PG8_MMA(ai, bj, At, Bt) do { __builtin_amdgcn_s_setprio(1); _Pragma("unroll") for (int m = 0; m < 4; ++m) _Pragma("unroll") for (int n = 0; n < 2; ++n) _Pragma("unroll") for (int k = 0; k < 2; ++k) \
;         acc[ai][bj][m][n] = __builtin_amdgcn_mfma_f32_16x16x32_bf16(Bt[n][k], At[m][k], acc[ai][bj][m][n], 0, 0, 0); __builtin_amdgcn_s_setprio(0); } while (0)
; #define PG8_WAIT_V(n) asm volatile("s_waitcnt vmcnt(" #n ")" ::: "memory")
; #define PG8_WAIT_L(n) asm volatile("s_waitcnt lgkmcnt(" #n ")" ::: "memory")
; #define PG8_BAR __builtin_amdgcn_s_barrier()
; #define PG8_SCHED __builtin_amdgcn_sched_barrier(0)
; template <class Epi, class Sched, bool ALIGN_EPI = false, bool SP2 = false>
; __device__ __forceinline__ void gemm_phase(PG8_LAS unsigned char* lds, const Gemm g, const Sched& S, const Epi& E) {
;     ...
;             PG8_LDB(B0, 1, 0); PG8_LDB(B1, 1, 1); PG8_SCHED; PG8_LDA(At, 1, 0); PG8_STAGE(PG8_SA(0, 1), a2 + hstep, voffA);
;             PG8_WAIT_V(8); PG8_WAIT_L(0); PG8_BAR; PG8_MMA(0, 0, At, B0); PG8_MMA(0, 1, At, B1); PG8_BAR; PG8_SCHED;
;             PG8_LDA(At, 1, 1); PG8_STAGE(PG8_SB(1, 0), b3, voffB); PG8_STAGE(PG8_SB(1, 1), b3 + hstep, voffB); PG8_STAGE(PG8_SA(1, 0), a3, voffA);
;             PG8_WAIT_V(8); PG8_WAIT_L(0); PG8_BAR; PG8_MMA(1, 0, At, B0); PG8_MMA(1, 1, At, B1); PG8_BAR; PG8_SCHED;
	s_add_i32 s27, 0, 0x18000
	v_add_u32_e32 v2, s27, v173
	s_add_i32 s29, 0, 0x1c000
	ds_read_b128 v[134:137], v2
	ds_read_b128 v[138:141], v2 offset:1024
	ds_read_b128 v[154:157], v2 offset:2048
	ds_read_b128 v[158:161], v2 offset:3072
	v_add_u32_e32 v2, s29, v173
	ds_read_b128 v[178:181], v2
	ds_read_b128 v[204:207], v2 offset:1024
	ds_read_b128 v[208:211], v2 offset:2048
	ds_read_b128 v[212:215], v2 offset:3072
	s_add_u32 s100, s44, 0x80
	s_addc_u32 s101, s45, 0
	s_add_u32 s44, s44, 0x40000
	s_addc_u32 s45, s45, 0
	s_mov_b32 m0, s57
	ds_read_b128 v[216:219], v177 offset:32768
	ds_read_b128 v[220:223], v177 offset:33792
	ds_read_b128 v[224:227], v177 offset:34816
	ds_read_b128 v[228:231], v177 offset:35840
	ds_read_b128 v[232:235], v177 offset:36864
	ds_read_b128 v[236:239], v177 offset:37888
	ds_read_b128 v[240:243], v177 offset:38912
	ds_read_b128 v[244:247], v177 offset:39936
	global_load_lds_dwordx4 v142, s[44:45]
	s_mov_b32 m0, s58
	s_nop 0
	global_load_lds_dwordx4 v146, s[44:45]
	s_waitcnt vmcnt(8)
	s_waitcnt lgkmcnt(0)
	s_barrier
	s_setprio 0
	s_waitcnt lgkmcnt(0)
	v_mfma_f32_16x16x32_bf16 v[130:133], v[134:137], v[216:219], v[130:133]
	v_mfma_f32_16x16x32_bf16 v[126:129], v[154:157], v[216:219], v[126:129]
	v_mfma_f32_16x16x32_bf16 v[122:125], v[134:137], v[224:227], v[122:125]
	v_mfma_f32_16x16x32_bf16 v[118:121], v[154:157], v[224:227], v[118:121]
	v_mfma_f32_16x16x32_bf16 v[114:117], v[134:137], v[232:235], v[114:117]
	v_mfma_f32_16x16x32_bf16 v[110:113], v[154:157], v[232:235], v[110:113]
	v_mfma_f32_16x16x32_bf16 v[106:109], v[134:137], v[240:243], v[106:109]
	v_mfma_f32_16x16x32_bf16 v[102:105], v[154:157], v[240:243], v[102:105]
	v_mfma_f32_16x16x32_bf16 v[130:133], v[138:141], v[220:223], v[130:133]
	v_mfma_f32_16x16x32_bf16 v[126:129], v[158:161], v[220:223], v[126:129]
	v_mfma_f32_16x16x32_bf16 v[122:125], v[138:141], v[228:231], v[122:125]
	v_mfma_f32_16x16x32_bf16 v[118:121], v[158:161], v[228:231], v[118:121]
	v_mfma_f32_16x16x32_bf16 v[114:117], v[138:141], v[236:239], v[114:117]
	v_mfma_f32_16x16x32_bf16 v[110:113], v[158:161], v[236:239], v[110:113]
	v_mfma_f32_16x16x32_bf16 v[106:109], v[138:141], v[244:247], v[106:109]
	v_mfma_f32_16x16x32_bf16 v[102:105], v[158:161], v[244:247], v[102:105]
	v_mfma_f32_16x16x32_bf16 v[98:101], v[178:181], v[216:219], v[98:101]
	v_mfma_f32_16x16x32_bf16 v[94:97], v[208:211], v[216:219], v[94:97]
	v_mfma_f32_16x16x32_bf16 v[90:93], v[178:181], v[224:227], v[90:93]
	v_mfma_f32_16x16x32_bf16 v[86:89], v[208:211], v[224:227], v[86:89]
	v_mfma_f32_16x16x32_bf16 v[82:85], v[178:181], v[232:235], v[82:85]
	v_mfma_f32_16x16x32_bf16 v[78:81], v[208:211], v[232:235], v[78:81]
	v_mfma_f32_16x16x32_bf16 v[74:77], v[178:181], v[240:243], v[74:77]
	v_mfma_f32_16x16x32_bf16 v[70:73], v[208:211], v[240:243], v[70:73]
	v_mfma_f32_16x16x32_bf16 v[98:101], v[204:207], v[220:223], v[98:101]
	v_mfma_f32_16x16x32_bf16 v[94:97], v[212:215], v[220:223], v[94:97]
	v_mfma_f32_16x16x32_bf16 v[90:93], v[204:207], v[228:231], v[90:93]
	v_mfma_f32_16x16x32_bf16 v[86:89], v[212:215], v[228:231], v[86:89]
	v_mfma_f32_16x16x32_bf16 v[82:85], v[204:207], v[236:239], v[82:85]
	v_mfma_f32_16x16x32_bf16 v[78:81], v[212:215], v[236:239], v[78:81]
	v_mfma_f32_16x16x32_bf16 v[74:77], v[204:207], v[244:247], v[74:77]
	v_mfma_f32_16x16x32_bf16 v[70:73], v[212:215], v[244:247], v[70:73]
	s_setprio 3
	s_barrier
	s_add_i32 s27, s27, s54
	s_add_i32 m0, s27, 0xffffff80
	ds_read_b128 v[216:219], v177 offset:49152
	ds_read_b128 v[220:223], v177 offset:50176
	ds_read_b128 v[224:227], v177 offset:51200
	ds_read_b128 v[228:231], v177 offset:52224
	ds_read_b128 v[232:235], v177 offset:53248
	ds_read_b128 v[236:239], v177 offset:54272
	ds_read_b128 v[240:243], v177 offset:55296
	ds_read_b128 v[244:247], v177 offset:56320
	global_load_lds_dwordx4 v144, s[42:43] offset:128
	s_add_i32 m0, s27, 0x1f80
	s_add_i32 s27, s29, s54
	global_load_lds_dwordx4 v148, s[42:43] offset:128
	s_add_u32 s42, s42, 0x40080
	s_addc_u32 s43, s43, 0
	s_mov_b32 m0, s27
	s_nop 0
	global_load_lds_dwordx4 v144, s[42:43]
	s_add_i32 m0, s27, 0x2000
	s_nop 0
	global_load_lds_dwordx4 v148, s[42:43]
	s_mov_b32 m0, s61
	s_nop 0
	global_load_lds_dwordx4 v142, s[100:101]
	s_mov_b32 m0, s62
	s_nop 0
	global_load_lds_dwordx4 v146, s[100:101]
	s_nop 0
	s_waitcnt vmcnt(8)
	s_waitcnt lgkmcnt(0)
	s_barrier
	s_setprio 0
	s_waitcnt lgkmcnt(0)
	v_mfma_f32_16x16x32_bf16 v[66:69], v[134:137], v[216:219], v[66:69]
	v_mfma_f32_16x16x32_bf16 v[62:65], v[154:157], v[216:219], v[62:65]
	v_mfma_f32_16x16x32_bf16 v[58:61], v[134:137], v[224:227], v[58:61]
	v_mfma_f32_16x16x32_bf16 v[54:57], v[154:157], v[224:227], v[54:57]
	v_mfma_f32_16x16x32_bf16 v[50:53], v[134:137], v[232:235], v[50:53]
	v_mfma_f32_16x16x32_bf16 v[46:49], v[154:157], v[232:235], v[46:49]
	v_mfma_f32_16x16x32_bf16 v[42:45], v[134:137], v[240:243], v[42:45]
	v_mfma_f32_16x16x32_bf16 v[38:41], v[154:157], v[240:243], v[38:41]
	v_mfma_f32_16x16x32_bf16 v[66:69], v[138:141], v[220:223], v[66:69]
	v_mfma_f32_16x16x32_bf16 v[62:65], v[158:161], v[220:223], v[62:65]
	v_mfma_f32_16x16x32_bf16 v[58:61], v[138:141], v[228:231], v[58:61]
	v_mfma_f32_16x16x32_bf16 v[54:57], v[158:161], v[228:231], v[54:57]
	v_mfma_f32_16x16x32_bf16 v[50:53], v[138:141], v[236:239], v[50:53]
	v_mfma_f32_16x16x32_bf16 v[46:49], v[158:161], v[236:239], v[46:49]
	v_mfma_f32_16x16x32_bf16 v[42:45], v[138:141], v[244:247], v[42:45]
	v_mfma_f32_16x16x32_bf16 v[38:41], v[158:161], v[244:247], v[38:41]
	v_mfma_f32_16x16x32_bf16 v[34:37], v[178:181], v[216:219], v[34:37]
	v_mfma_f32_16x16x32_bf16 v[30:33], v[208:211], v[216:219], v[30:33]
	v_mfma_f32_16x16x32_bf16 v[26:29], v[178:181], v[224:227], v[26:29]
	v_mfma_f32_16x16x32_bf16 v[22:25], v[208:211], v[224:227], v[22:25]
	v_mfma_f32_16x16x32_bf16 v[18:21], v[178:181], v[232:235], v[18:21]
	v_mfma_f32_16x16x32_bf16 v[14:17], v[208:211], v[232:235], v[14:17]
	v_mfma_f32_16x16x32_bf16 v[8:11], v[178:181], v[240:243], v[10:13]
	v_mfma_f32_16x16x32_bf16 v[4:7], v[208:211], v[240:243], v[4:7]
	v_mfma_f32_16x16x32_bf16 v[34:37], v[204:207], v[220:223], v[34:37]
	v_mfma_f32_16x16x32_bf16 v[30:33], v[212:215], v[220:223], v[30:33]
	v_mfma_f32_16x16x32_bf16 v[26:29], v[204:207], v[228:231], v[26:29]
	v_mfma_f32_16x16x32_bf16 v[22:25], v[212:215], v[228:231], v[22:25]
	v_mfma_f32_16x16x32_bf16 v[18:21], v[204:207], v[236:239], v[18:21]
	v_mfma_f32_16x16x32_bf16 v[14:17], v[212:215], v[236:239], v[14:17]
	v_mfma_f32_16x16x32_bf16 v[10:13], v[204:207], v[244:247], v[8:11]
	v_mfma_f32_16x16x32_bf16 v[6:9], v[212:215], v[244:247], v[4:7]
	s_setprio 3
	s_barrier
	s_add_i32 s26, s26, 2
	s_add_u32 s40, s40, 0x100
	s_addc_u32 s41, s41, 0
	s_add_u32 s11, s11, 0x100
	s_addc_u32 s13, s13, 0
	s_cmp_gt_u32 s26, 13
	s_cbranch_scc0 .LBB0_2096
	s_and_b64 vcc, exec, s[8:9]
	s_cbranch_vccz .LBB0_2099
	s_barrier

; #define PG8_STAGE(bufoff, gbase, voff) do { _Pragma("unroll") for (int _i = 0; _i < 2; ++_i) \
;         __builtin_amdgcn_global_load_lds((const unsigned*)((const char*)(gbase) + (voff)[_i]), (PG8_LAS unsigned*)(lds + (bufoff) + ldsw + _i * 8192), 16, 0, 0); } while (0)
; #define PG8_LDA(dst, b, h) do { _Pragma("unroll") for (int m = 0; m < 4; ++m) _Pragma("unroll") for (int k = 0; k < 2; ++k) dst[m][k] = *(const PG8_LAS bf16x8*)(lds + PG8_SA(b, h) + aoff + m * 2048 + k * 1024); } while (0)
; #define PG8_LDB(dst, b, h) do { _Pragma("unroll") for (int n = 0; n < 2; ++n) _Pragma("unroll") for (int k = 0; k < 2; ++k) dst[n][k] = *(const PG8_LAS bf16x8*)(lds + PG8_SB(b, h) + boff + n * 2048 + k * 1024); } while (0)
; #define PG8_MMA(ai, bj, At, Bt) do { __builtin_amdgcn_s_setprio(1); _Pragma("unroll") for (int m = 0; m < 4; ++m) _Pragma("unroll") for (int n = 0; n < 2; ++n) _Pragma("unroll") for (int k = 0; k < 2; ++k) \
;         acc[ai][bj][m][n] = __builtin_amdgcn_mfma_f32_16x16x32_bf16(Bt[n][k], At[m][k], acc[ai][bj][m][n], 0, 0, 0); __builtin_amdgcn_s_setprio(0); } while (0)
; #define PG8_WAIT_V(n) asm volatile("s_waitcnt vmcnt(" #n ")" ::: "memory")
; #define PG8_WAIT_L(n) asm volatile("s_waitcnt lgkmcnt(" #n ")" ::: "memory")
; template <class Epi, class Sched, bool ALIGN_EPI = false, bool SP2 = false>
; __device__ __forceinline__ void gemm_phase(PG8_LAS unsigned char* lds, const Gemm g, const Sched& S, const Epi& E) {
;     ...
;             const bool last = (t == nt - 2);
;             const char* a1 = cA + (size_t)(t + 1) * kstep;
;             const char* a2 = last ? nA : cA + (size_t)(t + 2) * kstep; const char* b2 = last ? nB : cB + (size_t)(t + 2) * kstep;
;             const char* a3 = a2 + kstep; const char* b3 = b2 + kstep;
;             if (last && has_next) S.a_ready(nxt);
;             if constexpr (SP2) {
;             PG8_LDB(B0, 0, 0); PG8_LDB(B1, 0, 1); PG8_SCHED; PG8_LDA(At, 0, 0); PG8_STAGE(PG8_SA(1, 1), a1 + hstep, voffA);
;             PG8_WAIT_V(8); PG8_WAIT_L(0); PG8_BAR; PG8_MMA(0, 0, At, B0); PG8_MMA(0, 1, At, B1); PG8_BAR; PG8_SCHED;
;             PG8_LDA(At, 0, 1); PG8_STAGE(PG8_SB(0, 0), b2, voffB); PG8_STAGE(PG8_SB(0, 1), b2 + hstep, voffB); PG8_STAGE(PG8_SA(0, 0), a2, voffA);
;             PG8_WAIT_V(8); PG8_WAIT_L(0); PG8_BAR; PG8_MMA(1, 0, At, B0); PG8_MMA(1, 1, At, B1); PG8_BAR; PG8_SCHED;
.LBB0_2185:
	s_add_u32 s42, s40, 0x100
	s_addc_u32 s43, s41, 0
	s_add_i32 s37, 0, 0x10000
	s_cmp_eq_u32 s31, 28
	s_cselect_b32 s47, s5, s43
	s_cselect_b32 s46, s4, s42
	v_add_u32_e32 v135, s37, v173
	s_cselect_b32 s45, s35, s29
	s_cselect_b32 s44, s34, s2
	s_add_i32 s39, 0, 0x14000
	ds_read_b128 v[142:145], v135
	ds_read_b128 v[146:149], v135 offset:1024
	ds_read_b128 v[150:153], v135 offset:2048
	ds_read_b128 v[154:157], v135 offset:3072
	v_add_u32_e32 v135, s39, v173
	ds_read_b128 v[158:161], v135
	ds_read_b128 v[174:177], v135 offset:1024
	ds_read_b128 v[180:183], v135 offset:2048
	ds_read_b128 v[204:207], v135 offset:3072
	v_lshl_add_u64 v[162:163], s[40:41], 0, v[138:139]
	s_add_i32 m0, s55, 0xc000
	ds_read_b128 v[208:211], v179
	ds_read_b128 v[212:215], v179 offset:1024
	ds_read_b128 v[216:219], v179 offset:2048
	ds_read_b128 v[220:223], v179 offset:3072
	ds_read_b128 v[224:227], v179 offset:4096
	ds_read_b128 v[228:231], v179 offset:5120
	ds_read_b128 v[232:235], v179 offset:6144
	ds_read_b128 v[236:239], v179 offset:7168
	global_load_lds_dwordx4 v[162:163], off
	v_lshl_add_u64 v[162:163], s[40:41], 0, v[140:141]
	s_add_i32 m0, s55, 0xe000
	s_nop 0
	global_load_lds_dwordx4 v[162:163], off
	s_waitcnt vmcnt(8)
	s_waitcnt lgkmcnt(0)
	s_barrier
	s_setprio 0
	s_waitcnt lgkmcnt(0)
	v_mfma_f32_16x16x32_bf16 v[128:131], v[142:145], v[208:211], v[128:131]
	v_mfma_f32_16x16x32_bf16 v[124:127], v[150:153], v[208:211], v[124:127]
	v_mfma_f32_16x16x32_bf16 v[112:115], v[142:145], v[216:219], v[112:115]
	v_mfma_f32_16x16x32_bf16 v[108:111], v[150:153], v[216:219], v[108:111]
	v_mfma_f32_16x16x32_bf16 v[96:99], v[142:145], v[224:227], v[96:99]
	v_mfma_f32_16x16x32_bf16 v[92:95], v[150:153], v[224:227], v[92:95]
	v_mfma_f32_16x16x32_bf16 v[80:83], v[142:145], v[232:235], v[80:83]
	v_mfma_f32_16x16x32_bf16 v[76:79], v[150:153], v[232:235], v[76:79]
	v_mfma_f32_16x16x32_bf16 v[128:131], v[146:149], v[212:215], v[128:131]
	v_mfma_f32_16x16x32_bf16 v[124:127], v[154:157], v[212:215], v[124:127]
	v_mfma_f32_16x16x32_bf16 v[112:115], v[146:149], v[220:223], v[112:115]
	v_mfma_f32_16x16x32_bf16 v[108:111], v[154:157], v[220:223], v[108:111]
	v_mfma_f32_16x16x32_bf16 v[96:99], v[146:149], v[228:231], v[96:99]
	v_mfma_f32_16x16x32_bf16 v[92:95], v[154:157], v[228:231], v[92:95]
	v_mfma_f32_16x16x32_bf16 v[80:83], v[146:149], v[236:239], v[80:83]
	v_mfma_f32_16x16x32_bf16 v[76:79], v[154:157], v[236:239], v[76:79]
	v_mfma_f32_16x16x32_bf16 v[120:123], v[158:161], v[208:211], v[120:123]
	v_mfma_f32_16x16x32_bf16 v[116:119], v[180:183], v[208:211], v[116:119]
	v_mfma_f32_16x16x32_bf16 v[104:107], v[158:161], v[216:219], v[104:107]
	v_mfma_f32_16x16x32_bf16 v[100:103], v[180:183], v[216:219], v[100:103]
	v_mfma_f32_16x16x32_bf16 v[88:91], v[158:161], v[224:227], v[88:91]
	v_mfma_f32_16x16x32_bf16 v[84:87], v[180:183], v[224:227], v[84:87]
	v_mfma_f32_16x16x32_bf16 v[72:75], v[158:161], v[232:235], v[72:75]
	v_mfma_f32_16x16x32_bf16 v[68:71], v[180:183], v[232:235], v[68:71]
	v_mfma_f32_16x16x32_bf16 v[120:123], v[174:177], v[212:215], v[120:123]
	v_mfma_f32_16x16x32_bf16 v[116:119], v[204:207], v[212:215], v[116:119]
	v_mfma_f32_16x16x32_bf16 v[104:107], v[174:177], v[220:223], v[104:107]
	v_mfma_f32_16x16x32_bf16 v[100:103], v[204:207], v[220:223], v[100:103]
	v_mfma_f32_16x16x32_bf16 v[88:91], v[174:177], v[228:231], v[88:91]
	v_mfma_f32_16x16x32_bf16 v[84:87], v[204:207], v[228:231], v[84:87]
	v_mfma_f32_16x16x32_bf16 v[72:75], v[174:177], v[236:239], v[72:75]
	v_mfma_f32_16x16x32_bf16 v[68:71], v[204:207], v[236:239], v[68:71]
	s_setprio 3
	s_barrier
	s_add_i32 s37, s37, s54
	s_mov_b32 m0, s37
	ds_read_b128 v[208:211], v179 offset:16384
	ds_read_b128 v[212:215], v179 offset:17408
	ds_read_b128 v[216:219], v179 offset:18432
	ds_read_b128 v[220:223], v179 offset:19456
	ds_read_b128 v[224:227], v179 offset:20480
	ds_read_b128 v[228:231], v179 offset:21504
	ds_read_b128 v[232:235], v179 offset:22528
	ds_read_b128 v[236:239], v179 offset:23552
	global_load_lds_dwordx4 v2, s[44:45]
	s_add_i32 m0, s37, 0x2000
	s_add_u32 s40, s44, 0x80000
	s_addc_u32 s41, s45, 0
	s_add_i32 s37, s39, s54
	global_load_lds_dwordx4 v132, s[44:45]
	s_mov_b32 m0, s37
	s_nop 0
	global_load_lds_dwordx4 v2, s[40:41]
	s_add_i32 m0, s37, 0x2000
	s_nop 0
	global_load_lds_dwordx4 v132, s[40:41]
	s_mov_b32 m0, s55
	s_nop 0
	global_load_lds_dwordx4 v2, s[46:47]
	s_mov_b32 m0, s56
	s_nop 0
	global_load_lds_dwordx4 v132, s[46:47]
	s_waitcnt vmcnt(8)
	s_waitcnt lgkmcnt(0)
	s_barrier
	s_setprio 0
	s_waitcnt lgkmcnt(0)
	v_mfma_f32_16x16x32_bf16 v[64:67], v[142:145], v[208:211], v[64:67]
	v_mfma_f32_16x16x32_bf16 v[60:63], v[150:153], v[208:211], v[60:63]
	v_mfma_f32_16x16x32_bf16 v[48:51], v[142:145], v[216:219], v[48:51]
	v_mfma_f32_16x16x32_bf16 v[44:47], v[150:153], v[216:219], v[44:47]
	v_mfma_f32_16x16x32_bf16 v[32:35], v[142:145], v[224:227], v[32:35]
	v_mfma_f32_16x16x32_bf16 v[28:31], v[150:153], v[224:227], v[28:31]
	v_mfma_f32_16x16x32_bf16 v[16:19], v[142:145], v[232:235], v[16:19]
	v_mfma_f32_16x16x32_bf16 v[12:15], v[150:153], v[232:235], v[12:15]
	v_mfma_f32_16x16x32_bf16 v[64:67], v[146:149], v[212:215], v[64:67]
	v_mfma_f32_16x16x32_bf16 v[60:63], v[154:157], v[212:215], v[60:63]
	v_mfma_f32_16x16x32_bf16 v[48:51], v[146:149], v[220:223], v[48:51]
	v_mfma_f32_16x16x32_bf16 v[44:47], v[154:157], v[220:223], v[44:47]
	v_mfma_f32_16x16x32_bf16 v[32:35], v[146:149], v[228:231], v[32:35]
	v_mfma_f32_16x16x32_bf16 v[28:31], v[154:157], v[228:231], v[28:31]
	v_mfma_f32_16x16x32_bf16 v[16:19], v[146:149], v[236:239], v[16:19]
	v_mfma_f32_16x16x32_bf16 v[12:15], v[154:157], v[236:239], v[12:15]
	v_mfma_f32_16x16x32_bf16 v[56:59], v[158:161], v[208:211], v[56:59]
	v_mfma_f32_16x16x32_bf16 v[52:55], v[180:183], v[208:211], v[52:55]
	v_mfma_f32_16x16x32_bf16 v[40:43], v[158:161], v[216:219], v[40:43]
	v_mfma_f32_16x16x32_bf16 v[36:39], v[180:183], v[216:219], v[36:39]
	v_mfma_f32_16x16x32_bf16 v[24:27], v[158:161], v[224:227], v[24:27]
	v_mfma_f32_16x16x32_bf16 v[20:23], v[180:183], v[224:227], v[20:23]
	v_mfma_f32_16x16x32_bf16 v[8:11], v[158:161], v[232:235], v[8:11]
	v_mfma_f32_16x16x32_bf16 v[4:7], v[180:183], v[232:235], v[4:7]
	v_mfma_f32_16x16x32_bf16 v[56:59], v[174:177], v[212:215], v[56:59]
	v_mfma_f32_16x16x32_bf16 v[52:55], v[204:207], v[212:215], v[52:55]
	v_mfma_f32_16x16x32_bf16 v[40:43], v[174:177], v[220:223], v[40:43]
	v_mfma_f32_16x16x32_bf16 v[36:39], v[204:207], v[220:223], v[36:39]
	v_mfma_f32_16x16x32_bf16 v[24:27], v[174:177], v[228:231], v[24:27]
	v_mfma_f32_16x16x32_bf16 v[20:23], v[204:207], v[228:231], v[20:23]
	v_mfma_f32_16x16x32_bf16 v[8:11], v[174:177], v[236:239], v[8:11]
	v_mfma_f32_16x16x32_bf16 v[4:7], v[204:207], v[236:239], v[4:7]
	s_setprio 3
	s_barrier
; #define PG8_STAGE(bufoff, gbase, voff) do { _Pragma("unroll") for (int _i = 0; _i < 2; ++_i) \
;         __builtin_amdgcn_global_load_lds((const unsigned*)((const char*)(gbase) + (voff)[_i]), (PG8_LAS unsigned*)(lds + (bufoff) + ldsw + _i * 8192), 16, 0, 0); } while (0)
; #define PG8_LDA(dst, b, h) do { _Pragma("unroll") for (int m = 0; m < 4; ++m) _Pragma("unroll") for (int k = 0; k < 2; ++k) dst[m][k] = *(const PG8_LAS bf16x8*)(lds + PG8_SA(b, h) + aoff + m * 2048 + k * 1024); } while (0)
; #define PG8_LDB(dst, b, h) do { _Pragma("unroll") for (int n = 0; n < 2; ++n) _Pragma("unroll") for (int k = 0; k < 2; ++k) dst[n][k] = *(const PG8_LAS bf16x8*)(lds + PG8_SB(b, h) + boff + n * 2048 + k * 1024); } while (0)
; #define PG8_MMA(ai, bj, At, Bt) do { __builtin_amdgcn_s_setprio(1); _Pragma("unroll") for (int m = 0; m < 4; ++m) _Pragma("unroll") for (int n = 0; n < 2; ++n) _Pragma("unroll") for (int k = 0; k < 2; ++k) \
;         acc[ai][bj][m][n] = __builtin_amdgcn_mfma_f32_16x16x32_bf16(Bt[n][k], At[m][k], acc[ai][bj][m][n], 0, 0, 0); __builtin_amdgcn_s_setprio(0); } while (0)
; #define PG8_WAIT_V(n) asm volatile("s_waitcnt vmcnt(" #n ")" ::: "memory")
; #define PG8_WAIT_L(n) asm volatile("s_waitcnt lgkmcnt(" #n ")" ::: "memory")
; #define PG8_BAR __builtin_amdgcn_s_barrier()
; #define PG8_SCHED __builtin_amdgcn_sched_barrier(0)
; template <class Epi, class Sched, bool ALIGN_EPI = false, bool SP2 = false>
; __device__ __forceinline__ void gemm_phase(PG8_LAS unsigned char* lds, const Gemm g, const Sched& S, const Epi& E) {
;     ...
;             PG8_LDB(B0, 1, 0); PG8_LDB(B1, 1, 1); PG8_SCHED; PG8_LDA(At, 1, 0); PG8_STAGE(PG8_SA(0, 1), a2 + hstep, voffA);
;             PG8_WAIT_V(8); PG8_WAIT_L(0); PG8_BAR; PG8_MMA(0, 0, At, B0); PG8_MMA(0, 1, At, B1); PG8_BAR; PG8_SCHED;
;             PG8_LDA(At, 1, 1); PG8_STAGE(PG8_SB(1, 0), b3, voffB); PG8_STAGE(PG8_SB(1, 1), b3 + hstep, voffB); PG8_STAGE(PG8_SA(1, 0), a3, voffA);
;             PG8_WAIT_V(8); PG8_WAIT_L(0); PG8_BAR; PG8_MMA(1, 0, At, B0); PG8_MMA(1, 1, At, B1); PG8_BAR; PG8_SCHED;
	s_add_i32 s37, 0, 0x18000
	v_add_u32_e32 v135, s37, v173
	s_add_i32 s39, 0, 0x1c000
	ds_read_b128 v[142:145], v135
	ds_read_b128 v[146:149], v135 offset:1024
	ds_read_b128 v[150:153], v135 offset:2048
	ds_read_b128 v[154:157], v135 offset:3072
	v_add_u32_e32 v135, s39, v173
	ds_read_b128 v[158:161], v135
	ds_read_b128 v[174:177], v135 offset:1024
	ds_read_b128 v[180:183], v135 offset:2048
	ds_read_b128 v[204:207], v135 offset:3072
	s_add_u32 s40, s46, 0x80000
	s_addc_u32 s41, s47, 0
	s_mov_b32 m0, s57
	ds_read_b128 v[208:211], v179 offset:32768
	ds_read_b128 v[212:215], v179 offset:33792
	ds_read_b128 v[216:219], v179 offset:34816
	ds_read_b128 v[220:223], v179 offset:35840
	ds_read_b128 v[224:227], v179 offset:36864
	ds_read_b128 v[228:231], v179 offset:37888
	ds_read_b128 v[232:235], v179 offset:38912
	ds_read_b128 v[236:239], v179 offset:39936
	global_load_lds_dwordx4 v2, s[40:41]
	s_mov_b32 m0, s58
	s_nop 0
	global_load_lds_dwordx4 v132, s[40:41]
	s_nop 0
	s_waitcnt vmcnt(8)
	s_waitcnt lgkmcnt(0)
	s_barrier
	s_setprio 0
	s_waitcnt lgkmcnt(0)
	v_mfma_f32_16x16x32_bf16 v[128:131], v[142:145], v[208:211], v[128:131]
	v_mfma_f32_16x16x32_bf16 v[124:127], v[150:153], v[208:211], v[124:127]
	v_mfma_f32_16x16x32_bf16 v[112:115], v[142:145], v[216:219], v[112:115]
	v_mfma_f32_16x16x32_bf16 v[108:111], v[150:153], v[216:219], v[108:111]
	v_mfma_f32_16x16x32_bf16 v[96:99], v[142:145], v[224:227], v[96:99]
	v_mfma_f32_16x16x32_bf16 v[92:95], v[150:153], v[224:227], v[92:95]
	v_mfma_f32_16x16x32_bf16 v[80:83], v[142:145], v[232:235], v[80:83]
	v_mfma_f32_16x16x32_bf16 v[76:79], v[150:153], v[232:235], v[76:79]
	v_mfma_f32_16x16x32_bf16 v[128:131], v[146:149], v[212:215], v[128:131]
	v_mfma_f32_16x16x32_bf16 v[124:127], v[154:157], v[212:215], v[124:127]
	v_mfma_f32_16x16x32_bf16 v[112:115], v[146:149], v[220:223], v[112:115]
	v_mfma_f32_16x16x32_bf16 v[108:111], v[154:157], v[220:223], v[108:111]
	v_mfma_f32_16x16x32_bf16 v[96:99], v[146:149], v[228:231], v[96:99]
	v_mfma_f32_16x16x32_bf16 v[92:95], v[154:157], v[228:231], v[92:95]
	v_mfma_f32_16x16x32_bf16 v[80:83], v[146:149], v[236:239], v[80:83]
	v_mfma_f32_16x16x32_bf16 v[76:79], v[154:157], v[236:239], v[76:79]
	v_mfma_f32_16x16x32_bf16 v[120:123], v[158:161], v[208:211], v[120:123]
	v_mfma_f32_16x16x32_bf16 v[116:119], v[180:183], v[208:211], v[116:119]
	v_mfma_f32_16x16x32_bf16 v[104:107], v[158:161], v[216:219], v[104:107]
	v_mfma_f32_16x16x32_bf16 v[100:103], v[180:183], v[216:219], v[100:103]
	v_mfma_f32_16x16x32_bf16 v[88:91], v[158:161], v[224:227], v[88:91]
	v_mfma_f32_16x16x32_bf16 v[84:87], v[180:183], v[224:227], v[84:87]
	v_mfma_f32_16x16x32_bf16 v[72:75], v[158:161], v[232:235], v[72:75]
	v_mfma_f32_16x16x32_bf16 v[68:71], v[180:183], v[232:235], v[68:71]
	v_mfma_f32_16x16x32_bf16 v[120:123], v[174:177], v[212:215], v[120:123]
	v_mfma_f32_16x16x32_bf16 v[116:119], v[204:207], v[212:215], v[116:119]
	v_mfma_f32_16x16x32_bf16 v[104:107], v[174:177], v[220:223], v[104:107]
	v_mfma_f32_16x16x32_bf16 v[100:103], v[204:207], v[220:223], v[100:103]
	v_mfma_f32_16x16x32_bf16 v[88:91], v[174:177], v[228:231], v[88:91]
	v_mfma_f32_16x16x32_bf16 v[84:87], v[204:207], v[228:231], v[84:87]
	v_mfma_f32_16x16x32_bf16 v[72:75], v[174:177], v[236:239], v[72:75]
	v_mfma_f32_16x16x32_bf16 v[68:71], v[204:207], v[236:239], v[68:71]
	s_setprio 3
	s_barrier
	s_add_i32 s37, s37, s54
	s_add_i32 m0, s37, 0xffffff80
	ds_read_b128 v[208:211], v179 offset:49152
	ds_read_b128 v[212:215], v179 offset:50176
	ds_read_b128 v[216:219], v179 offset:51200
	ds_read_b128 v[220:223], v179 offset:52224
	ds_read_b128 v[224:227], v179 offset:53248
	ds_read_b128 v[228:231], v179 offset:54272
	ds_read_b128 v[232:235], v179 offset:55296
	ds_read_b128 v[236:239], v179 offset:56320
	global_load_lds_dwordx4 v2, s[44:45] offset:128
	s_add_i32 m0, s37, 0x1f80
	s_add_u32 s40, s44, 0x80080
	s_addc_u32 s41, s45, 0
	s_add_i32 s37, s39, s54
	global_load_lds_dwordx4 v132, s[44:45] offset:128
	s_mov_b32 m0, s37
	s_nop 0
	global_load_lds_dwordx4 v2, s[40:41]
	s_add_i32 m0, s37, 0x2000
	s_nop 0
	global_load_lds_dwordx4 v132, s[40:41]
	s_add_i32 m0, s60, 0xffffff80
	s_nop 0
	global_load_lds_dwordx4 v2, s[46:47] offset:128
	s_add_i32 m0, s61, 0xffffff80
	s_nop 0
	global_load_lds_dwordx4 v132, s[46:47] offset:128
	s_nop 0
	s_waitcnt vmcnt(8)
	s_waitcnt lgkmcnt(0)
	s_barrier
	s_setprio 0
	s_waitcnt lgkmcnt(0)
	v_mfma_f32_16x16x32_bf16 v[64:67], v[142:145], v[208:211], v[64:67]
	v_mfma_f32_16x16x32_bf16 v[60:63], v[150:153], v[208:211], v[60:63]
	v_mfma_f32_16x16x32_bf16 v[48:51], v[142:145], v[216:219], v[48:51]
	v_mfma_f32_16x16x32_bf16 v[44:47], v[150:153], v[216:219], v[44:47]
	v_mfma_f32_16x16x32_bf16 v[32:35], v[142:145], v[224:227], v[32:35]
	v_mfma_f32_16x16x32_bf16 v[28:31], v[150:153], v[224:227], v[28:31]
	v_mfma_f32_16x16x32_bf16 v[16:19], v[142:145], v[232:235], v[16:19]
	v_mfma_f32_16x16x32_bf16 v[12:15], v[150:153], v[232:235], v[12:15]
	v_mfma_f32_16x16x32_bf16 v[64:67], v[146:149], v[212:215], v[64:67]
	v_mfma_f32_16x16x32_bf16 v[60:63], v[154:157], v[212:215], v[60:63]
	v_mfma_f32_16x16x32_bf16 v[48:51], v[146:149], v[220:223], v[48:51]
	v_mfma_f32_16x16x32_bf16 v[44:47], v[154:157], v[220:223], v[44:47]
	v_mfma_f32_16x16x32_bf16 v[32:35], v[146:149], v[228:231], v[32:35]
	v_mfma_f32_16x16x32_bf16 v[28:31], v[154:157], v[228:231], v[28:31]
	v_mfma_f32_16x16x32_bf16 v[16:19], v[146:149], v[236:239], v[16:19]
	v_mfma_f32_16x16x32_bf16 v[12:15], v[154:157], v[236:239], v[12:15]
	v_mfma_f32_16x16x32_bf16 v[56:59], v[158:161], v[208:211], v[56:59]
	v_mfma_f32_16x16x32_bf16 v[52:55], v[180:183], v[208:211], v[52:55]
	v_mfma_f32_16x16x32_bf16 v[40:43], v[158:161], v[216:219], v[40:43]
	v_mfma_f32_16x16x32_bf16 v[36:39], v[180:183], v[216:219], v[36:39]
	v_mfma_f32_16x16x32_bf16 v[24:27], v[158:161], v[224:227], v[24:27]
	v_mfma_f32_16x16x32_bf16 v[20:23], v[180:183], v[224:227], v[20:23]
	v_mfma_f32_16x16x32_bf16 v[8:11], v[158:161], v[232:235], v[8:11]
	v_mfma_f32_16x16x32_bf16 v[4:7], v[180:183], v[232:235], v[4:7]
	v_mfma_f32_16x16x32_bf16 v[56:59], v[174:177], v[212:215], v[56:59]
	v_mfma_f32_16x16x32_bf16 v[52:55], v[204:207], v[212:215], v[52:55]
	v_mfma_f32_16x16x32_bf16 v[40:43], v[174:177], v[220:223], v[40:43]
	v_mfma_f32_16x16x32_bf16 v[36:39], v[204:207], v[220:223], v[36:39]
	v_mfma_f32_16x16x32_bf16 v[24:27], v[174:177], v[228:231], v[24:27]
	v_mfma_f32_16x16x32_bf16 v[20:23], v[204:207], v[228:231], v[20:23]
	v_mfma_f32_16x16x32_bf16 v[8:11], v[174:177], v[236:239], v[8:11]
	v_mfma_f32_16x16x32_bf16 v[4:7], v[204:207], v[236:239], v[4:7]
	s_setprio 3
	s_barrier
	s_add_i32 s31, s31, 2
	s_add_u32 s2, s2, 0x100
	s_addc_u32 s29, s29, 0
	s_cmp_gt_u32 s31, 29
	s_mov_b64 s[40:41], s[42:43]
	s_cbranch_scc0 .LBB0_2185
	s_and_b64 vcc, exec, s[26:27]
	s_cbranch_vccz .LBB0_2188
	s_barrier
